# retention q written by the in-projection epilogue in MFMA-fragment order: coalesced q fragment loads in ret_p and ret_scan; ret_p loop loads pipelined
# speedup vs baseline: 1.0366x; 1.0197x over previous
; __device__ __forceinline__ void ret_scan_unit(unsigned char* smem, const bf16_t* __restrict__ Q, const bf16_t* __restrict__ K, const bf16_t* __restrict__ V,
;                                               const bf16_t* __restrict__ Pt, bf16_t* OX, int b, int h, int dvs, const float* lg) {
;     ...
;         for (int step = 0; step < 18; ++step) {
;             int ci;
;             if (step < 2) ci = dir ? 1 - step : step; else ci = dir ? 2 + (15 - (step - 2)) : step;
;             const int row0 = ci < 2 ? ML + b * CTXL + 128 * ci : b * SEQL + 128 * (ci - 2);
;             int tid = tid0; asm volatile("" : "+v"(tid));
;             const int lane = tid & 63, w = __builtin_amdgcn_readfirstlane(tid >> 6), h2 = lane >> 5, l31 = lane & 31, dvb = w & 1, ib = w >> 1;
;             const int trl = ((lane >> 4) & 1) * 32 + (lane & 3) * 8;
;             const int trr = ((lane & 15) >> 2);
;             bf16x8 qf[16], pfr[8];
;             {
;                 const bf16_t* qp = Q + (size_t)(row0 + 32 * ib + l31) * 1024 + h * 256 + 8 * h2;
; #pragma unroll
;                 for (int f = 0; f < 16; ++f) qf[f] = *(const bf16x8*)(qp + 16 * f);
.LBB0_391:
	s_lshl_b32 s2, s92, 2
	s_or_b32 s22, s2, s89
	s_lshl_b64 s[2:3], s[22:23], 2
	s_add_u32 s2, s78, s2
	s_addc_u32 s3, s79, s3
	global_load_dword v10, v181, s[2:3]
	v_add_co_u32_e64 v11, s[38:39], s92, -1
	s_lshl_b32 s2, s92, 5
	s_xor_b64 s[16:17], s[38:39], -1
	s_add_i32 s2, s2, s88
	s_waitcnt vmcnt(0)
	v_mov_b32_e32 v151, v183
	s_and_b64 vcc, s[38:39], exec
	s_mul_hi_i32 s93, s2, 18
	v_readfirstlane_b32 s3, v151
	s_mul_i32 s94, s2, 18
	s_cselect_b32 s2, 0x80, 0
	s_ashr_i32 s4, s3, 2
	s_or_b32 s6, s2, s91
	s_and_b32 s2, s4, 0xffffffe0
	v_and_b32_e32 v73, 31, v151
	s_add_i32 s7, s2, s6
	v_or_b32_e32 v0, s7, v73
	v_ashrrev_i32_e32 v1, 31, v0
	v_bfe_u32 v155, v151, 5, 1
	v_lshlrev_b64 v[0:1], 11, v[0:1]
	v_cndmask_b32_e64 v6, 0, 1, s[38:39]
	v_lshl_add_u64 v[0:1], s[46:47], 0, v[0:1]
	v_lshlrev_b32_e32 v180, 4, v155
	v_mov_b32_e32 v8, s4
	s_lshl_b32 s100, s89, 14
	s_add_u32 s100, s80, s100
	s_addc_u32 s101, s81, 0
	s_lshl_b32 s98, s7, 11
	s_add_u32 s100, s100, s98
	s_addc_u32 s101, s101, 0
	v_lshlrev_b32_e32 v238, 4, v73
	v_lshl_or_b32 v238, v155, 9, v238

; __device__ __forceinline__ void ret_scan_unit(unsigned char* smem, const bf16_t* __restrict__ Q, const bf16_t* __restrict__ K, const bf16_t* __restrict__ V,
;                                               const bf16_t* __restrict__ Pt, bf16_t* OX, int b, int h, int dvs, const float* lg) {
;     ...
;                 const bf16_t* qp = Q + (size_t)(row0 + 32 * ib + l31) * 1024 + h * 256 + 8 * h2;
; #pragma unroll
;                 for (int f = 0; f < 16; ++f) qf[f] = *(const bf16x8*)(qp + 16 * f);
	v_or_b32_e32 v6, s94, v6
	v_mov_b32_e32 v7, s93
	v_bfi_b32 v8, s1, v8, v151
	global_load_dwordx4 v[0:3], v238, s[100:101]
	global_load_dwordx4 v[144:147], v238, s[100:101] offset:1024
	global_load_dwordx4 v[136:139], v238, s[100:101] offset:2048
	global_load_dwordx4 v[128:131], v238, s[100:101] offset:3072
	s_add_u32 s100, s100, 0x1000
	s_addc_u32 s101, s101, 0

; __device__ __forceinline__ void ret_scan_unit(unsigned char* smem, const bf16_t* __restrict__ Q, const bf16_t* __restrict__ K, const bf16_t* __restrict__ V,
;                                               const bf16_t* __restrict__ Pt, bf16_t* OX, int b, int h, int dvs, const float* lg) {
;     ...
;                 for (int f = 0; f < 16; ++f) qf[f] = *(const bf16x8*)(qp + 16 * f);
	global_load_dwordx4 v[124:127], v238, s[100:101]
	global_load_dwordx4 v[120:123], v238, s[100:101] offset:1024
	global_load_dwordx4 v[116:119], v238, s[100:101] offset:2048
	global_load_dwordx4 v[112:115], v238, s[100:101] offset:3072
	s_add_u32 s100, s100, 0x1000
	s_addc_u32 s101, s101, 0

; __device__ __forceinline__ void ret_scan_unit(unsigned char* smem, const bf16_t* __restrict__ Q, const bf16_t* __restrict__ K, const bf16_t* __restrict__ V,
;                                               const bf16_t* __restrict__ Pt, bf16_t* OX, int b, int h, int dvs, const float* lg) {
;     ...
;                 for (int f = 0; f < 16; ++f) qf[f] = *(const bf16x8*)(qp + 16 * f);
	global_load_dwordx4 v[108:111], v238, s[100:101]
	global_load_dwordx4 v[104:107], v238, s[100:101] offset:1024
	global_load_dwordx4 v[100:103], v238, s[100:101] offset:2048
	global_load_dwordx4 v[96:99], v238, s[100:101] offset:3072
	s_add_u32 s100, s100, 0x1000
	s_addc_u32 s101, s101, 0

; __device__ __forceinline__ void ret_scan_unit(unsigned char* smem, const bf16_t* __restrict__ Q, const bf16_t* __restrict__ K, const bf16_t* __restrict__ V,
;                                               const bf16_t* __restrict__ Pt, bf16_t* OX, int b, int h, int dvs, const float* lg) {
;     ...
;                 for (int f = 0; f < 16; ++f) qf[f] = *(const bf16x8*)(qp + 16 * f);
;                 const bf16_t* pp = Pt + ((size_t)((dir * 8 + b) * 4 + h) * 18 + ci) * 16384 + (size_t)(32 * ib + l31) * 128 + 8 * h2;
; #pragma unroll
;                 for (int ks = 0; ks < 8; ++ks) pfr[ks] = *(const bf16x8*)(pp + ks * 16);
	global_load_dwordx4 v[92:95], v238, s[100:101]
	global_load_dwordx4 v[88:91], v238, s[100:101] offset:1024
	v_lshlrev_b64 v[6:7], 15, v[6:7]
	v_ashrrev_i32_e32 v9, 31, v8
	v_lshl_add_u64 v[6:7], s[44:45], 0, v[6:7]
	v_lshlrev_b64 v[8:9], 8, v[8:9]
	v_lshl_add_u64 v[6:7], v[6:7], 0, v[8:9]
	v_lshl_add_u64 v[6:7], v[6:7], 0, v[180:181]
	global_load_dwordx4 v[44:47], v[6:7], off
	global_load_dwordx4 v[40:43], v[6:7], off offset:32
	global_load_dwordx4 v[36:39], v[6:7], off offset:64
	global_load_dwordx4 v[32:35], v[6:7], off offset:96
	global_load_dwordx4 v[28:31], v[6:7], off offset:128
	global_load_dwordx4 v[24:27], v[6:7], off offset:160
	global_load_dwordx4 v[20:23], v[6:7], off offset:192
	global_load_dwordx4 v[16:19], v[6:7], off offset:224
	global_load_dwordx4 v[140:143], v238, s[100:101] offset:2048
	global_load_dwordx4 v[132:135], v238, s[100:101] offset:3072

; __device__ __forceinline__ void ret_scan_unit(unsigned char* smem, const bf16_t* __restrict__ Q, const bf16_t* __restrict__ K, const bf16_t* __restrict__ V,
;                                               const bf16_t* __restrict__ Pt, bf16_t* OX, int b, int h, int dvs, const float* lg) {
;     ...
;         const float lgd = __uint_as_float(__builtin_amdgcn_readfirstlane(__float_as_uint(lg[dir * 4 + h])));
;         const float gC = __uint_as_float(__builtin_amdgcn_readfirstlane(__float_as_uint(__builtin_amdgcn_exp2f(128.f * lgd))));
;     ...
;             bf16_t* op = OX + (size_t)(row0 + 32 * ib + (l31 & 3) + 4 * h2) * 2048 + h * 512 + dvs * 64 + dvb * 32 + 4 * (l31 >> 2);
;             u32x2 prev2[4];
;             if (dir == 0) {
; #pragma unroll
;                 for (int j = 0; j < 4; ++j) prev2[j] = *(const u32x2*)(op + (size_t)(8 * j) * 2048);
	v_and_b32_e32 v4, 3, v151
	v_lshlrev_b32_e32 v154, 2, v155
	v_or3_b32 v4, v154, v4, s7
	v_ashrrev_i32_e32 v5, 31, v4
	s_bfe_u32 s8, s3, 0x10006
	v_lshlrev_b64 v[4:5], 12, v[4:5]
	v_and_b32_e32 v6, 28, v151
	s_lshl_b32 s22, s8, 6
	v_lshl_add_u64 v[4:5], s[52:53], 0, v[4:5]
	v_lshl_add_u64 v[4:5], v[4:5], 0, s[22:23]
	v_lshlrev_b32_e32 v180, 1, v6
	s_mov_b32 s4, 0
	v_readfirstlane_b32 s95, v11
	s_lshl_b32 s5, s8, 5
	v_lshl_add_u64 v[148:149], v[4:5], 0, v[180:181]
	s_waitcnt vmcnt(0)
	v_readfirstlane_b32 s96, v10
	s_nop 1
	v_mul_f32_e32 v7, s96, v199
	v_exp_f32_e32 v7, v7
	s_nop 0
	v_readfirstlane_b32 s58, v7
	s_cbranch_vccnz .LBB0_393
	v_add_co_u32_e32 v4, vcc, 0x8000, v148
	s_movk_i32 s4, 0x80
	s_nop 0
	v_addc_co_u32_e32 v5, vcc, 0, v149, vcc
	v_add_co_u32_e32 v6, vcc, 0x10000, v148
	s_nop 1
	v_addc_co_u32_e32 v7, vcc, 0, v149, vcc
	v_add_co_u32_e32 v8, vcc, 0x18000, v148
	s_nop 1
	v_addc_co_u32_e32 v9, vcc, 0, v149, vcc
	global_load_dwordx2 v[184:185], v[148:149], off
	global_load_dwordx2 v[186:187], v[4:5], off
	global_load_dwordx2 v[188:189], v[6:7], off
	global_load_dwordx2 v[190:191], v[8:9], off

; __device__ __forceinline__ void ret_scan_unit(unsigned char* smem, const bf16_t* __restrict__ Q, const bf16_t* __restrict__ K, const bf16_t* __restrict__ V,
;                                               const bf16_t* __restrict__ Pt, bf16_t* OX, int b, int h, int dvs, const float* lg) {
;     ...
;             int ci;
;             if (step < 2) ci = dir ? 1 - step : step; else ci = dir ? 2 + (15 - (step - 2)) : step;
;             const int row0 = ci < 2 ? ML + b * CTXL + 128 * ci : b * SEQL + 128 * (ci - 2);
;             int tid = tid0; asm volatile("" : "+v"(tid));
;             const int lane = tid & 63, w = __builtin_amdgcn_readfirstlane(tid >> 6), h2 = lane >> 5, l31 = lane & 31, dvb = w & 1, ib = w >> 1;
;             const int trl = ((lane >> 4) & 1) * 32 + (lane & 3) * 8;
;             const int trr = ((lane & 15) >> 2);
;             bf16x8 qf[16], pfr[8];
;             {
;                 const bf16_t* qp = Q + (size_t)(row0 + 32 * ib + l31) * 1024 + h * 256 + 8 * h2;
; #pragma unroll
;                 for (int f = 0; f < 16; ++f) qf[f] = *(const bf16x8*)(qp + 16 * f);
.LBB0_403:
	s_add_i32 s5, s4, -1
	s_sub_i32 s6, s8, 17
	s_and_b64 s[2:3], s[38:39], exec
	s_cselect_b32 s6, s6, s5
	s_add_i32 s7, s8, 1
	s_and_b64 s[2:3], s[38:39], exec
	s_cselect_b32 s2, s7, s5
	s_cmp_lt_u32 s5, 2
	s_cselect_b32 s3, s6, s2
	s_lshl_b32 s2, s3, 7
	s_or_b32 s6, s2, s91
	s_add_i32 s2, s2, s90
	s_cmp_lt_u32 s3, 2
	v_mov_b32_e32 v209, v183
	s_cselect_b32 s6, s6, s2
	s_nop 0
	v_readfirstlane_b32 s2, v209
	s_ashr_i32 s9, s2, 2
	s_and_b32 s7, s9, 0xffffffe0
	v_and_b32_e32 v37, 31, v209
	s_add_i32 s6, s6, s7
	v_or_b32_e32 v32, s6, v37
	v_ashrrev_i32_e32 v33, 31, v32
	v_bfe_u32 v36, v209, 5, 1
	v_lshlrev_b64 v[32:33], 11, v[32:33]
	v_lshl_add_u64 v[32:33], s[46:47], 0, v[32:33]
	v_lshlrev_b32_e32 v180, 4, v36
	s_lshl_b32 s100, s89, 14
	s_add_u32 s100, s80, s100
	s_addc_u32 s101, s81, 0
	s_lshl_b32 s98, s6, 11
	s_add_u32 s100, s100, s98
	s_addc_u32 s101, s101, 0
	v_lshlrev_b32_e32 v38, 4, v37
	v_lshl_or_b32 v38, v36, 9, v38

; __device__ __forceinline__ void ret_scan_unit(unsigned char* smem, const bf16_t* __restrict__ Q, const bf16_t* __restrict__ K, const bf16_t* __restrict__ V,
;                                               const bf16_t* __restrict__ Pt, bf16_t* OX, int b, int h, int dvs, const float* lg) {
;     ...
;                 for (int f = 0; f < 16; ++f) qf[f] = *(const bf16x8*)(qp + 16 * f);
	global_load_dwordx4 v[32:35], v38, s[100:101]
	global_load_dwordx4 v[176:179], v38, s[100:101] offset:1024
	global_load_dwordx4 v[172:175], v38, s[100:101] offset:2048
	global_load_dwordx4 v[168:171], v38, s[100:101] offset:3072
	s_add_u32 s100, s100, 0x1000
	s_addc_u32 s101, s101, 0

; __device__ __forceinline__ void ret_scan_unit(unsigned char* smem, const bf16_t* __restrict__ Q, const bf16_t* __restrict__ K, const bf16_t* __restrict__ V,
;                                               const bf16_t* __restrict__ Pt, bf16_t* OX, int b, int h, int dvs, const float* lg) {
;     ...
;                 for (int f = 0; f < 16; ++f) qf[f] = *(const bf16x8*)(qp + 16 * f);
	global_load_dwordx4 v[164:167], v38, s[100:101]
	global_load_dwordx4 v[160:163], v38, s[100:101] offset:1024
	global_load_dwordx4 v[156:159], v38, s[100:101] offset:2048
	global_load_dwordx4 v[152:155], v38, s[100:101] offset:3072
	s_add_u32 s100, s100, 0x1000
	s_addc_u32 s101, s101, 0

; __device__ __forceinline__ void ret_scan_unit(unsigned char* smem, const bf16_t* __restrict__ Q, const bf16_t* __restrict__ K, const bf16_t* __restrict__ V,
;                                               const bf16_t* __restrict__ Pt, bf16_t* OX, int b, int h, int dvs, const float* lg) {
;     ...
;                 for (int f = 0; f < 16; ++f) qf[f] = *(const bf16x8*)(qp + 16 * f);
	global_load_dwordx4 v[148:151], v38, s[100:101]
	global_load_dwordx4 v[144:147], v38, s[100:101] offset:1024
	global_load_dwordx4 v[140:143], v38, s[100:101] offset:2048
	global_load_dwordx4 v[136:139], v38, s[100:101] offset:3072
	s_add_u32 s100, s100, 0x1000
	s_addc_u32 s101, s101, 0

; __device__ __forceinline__ void ret_scan_unit(unsigned char* smem, const bf16_t* __restrict__ Q, const bf16_t* __restrict__ K, const bf16_t* __restrict__ V,
;                                               const bf16_t* __restrict__ Pt, bf16_t* OX, int b, int h, int dvs, const float* lg) {
;     ...
;                 for (int f = 0; f < 16; ++f) qf[f] = *(const bf16x8*)(qp + 16 * f);
;                 const bf16_t* pp = Pt + ((size_t)((dir * 8 + b) * 4 + h) * 18 + ci) * 16384 + (size_t)(32 * ib + l31) * 128 + 8 * h2;
; #pragma unroll
;                 for (int ks = 0; ks < 8; ++ks) pfr[ks] = *(const bf16x8*)(pp + ks * 16);
;             }
;             bf16_t* op = OX + (size_t)(row0 + 32 * ib + (l31 & 3) + 4 * h2) * 2048 + h * 512 + dvs * 64 + dvb * 32 + 4 * (l31 >> 2);
;             u32x2 prev2[4];
;             if (dir == 0) {
; #pragma unroll
;                 for (int j = 0; j < 4; ++j) prev2[j] = *(const u32x2*)(op + (size_t)(8 * j) * 2048);
	global_load_dwordx4 v[132:135], v38, s[100:101]
	global_load_dwordx4 v[128:131], v38, s[100:101] offset:1024
	global_load_dwordx4 v[124:127], v38, s[100:101] offset:2048
	global_load_dwordx4 v[120:123], v38, s[100:101] offset:3072
	s_add_u32 s42, s94, s3
	s_addc_u32 s43, s93, 0
	v_mov_b32_e32 v38, s9
	s_lshl_b64 s[42:43], s[42:43], 15
	v_bfi_b32 v38, s1, v38, v209
	s_add_u32 s42, s44, s42
	v_ashrrev_i32_e32 v39, 31, v38
	s_addc_u32 s43, s45, s43
	v_lshlrev_b64 v[38:39], 8, v[38:39]
	v_lshl_add_u64 v[38:39], s[42:43], 0, v[38:39]
	v_lshl_add_u64 v[38:39], v[38:39], 0, v[180:181]
	global_load_dwordx4 v[116:119], v[38:39], off
	global_load_dwordx4 v[112:115], v[38:39], off offset:32
	global_load_dwordx4 v[108:111], v[38:39], off offset:64
	global_load_dwordx4 v[104:107], v[38:39], off offset:96
	global_load_dwordx4 v[100:103], v[38:39], off offset:128
	global_load_dwordx4 v[96:99], v[38:39], off offset:160
	global_load_dwordx4 v[92:95], v[38:39], off offset:192
	global_load_dwordx4 v[88:91], v[38:39], off offset:224
	v_and_b32_e32 v38, 3, v209
	v_lshlrev_b32_e32 v211, 2, v36
	v_or3_b32 v38, v211, v38, s6
	v_ashrrev_i32_e32 v39, 31, v38
	s_bfe_u32 s3, s2, 0x10006
	v_lshlrev_b64 v[38:39], 12, v[38:39]
	v_lshl_add_u64 v[38:39], s[52:53], 0, v[38:39]
	s_lshl_b32 s22, s3, 6
	v_and_b32_e32 v40, 28, v209
	v_lshl_add_u64 v[38:39], v[38:39], 0, s[22:23]
	v_lshlrev_b32_e32 v180, 1, v40
	s_and_b64 vcc, exec, s[40:41]
	v_lshl_add_u64 v[192:193], v[38:39], 0, v[180:181]
	s_cbranch_vccnz .LBB0_405
	v_add_co_u32_e32 v38, vcc, 0x8000, v192
	s_nop 1
	v_addc_co_u32_e32 v39, vcc, 0, v193, vcc
	v_add_co_u32_e32 v40, vcc, 0x10000, v192
	s_nop 1
	v_addc_co_u32_e32 v41, vcc, 0, v193, vcc
	v_add_co_u32_e32 v42, vcc, 0x18000, v192
	s_nop 1
	v_addc_co_u32_e32 v43, vcc, 0, v193, vcc
	global_load_dwordx2 v[184:185], v[192:193], off
	global_load_dwordx2 v[186:187], v[38:39], off
	global_load_dwordx2 v[188:189], v[40:41], off
	global_load_dwordx2 v[190:191], v[42:43], off

; __device__ __forceinline__ void ret_p_unit(const bf16_t* __restrict__ Q, const bf16_t* __restrict__ K, bf16_t* Pt, int b, int h, int ci, float lgf, float lgb) {
;     ...
;     const int row0 = ci < 2 ? ML + b * CTXL + 128 * ci : b * SEQL + 128 * (ci - 2);
;     const int ib = w & 3, jh = w >> 2;
;     const bf16_t* qp = Q + (size_t)(row0 + 32 * ib + l31) * 1024 + h * 256 + h2 * 8;
;     f32x16 s[2];
; #pragma unroll
;     for (int jb = 0; jb < 2; ++jb)
; #pragma unroll
;         for (int r = 0; r < 16; ++r) s[jb][r] = 0.f;
;     const bf16_t* kp0 = K + (size_t)(row0 + 64 * jh + l31) * 1024 + h * 256 + h2 * 8;
; #pragma unroll 4
;     for (int ks = 0; ks < 16; ++ks) {
;         const bf16x8 a = *(const bf16x8*)(qp + ks * 16);
;         const bf16x8 b0 = *(const bf16x8*)(kp0 + ks * 16), b1 = *(const bf16x8*)(kp0 + 32 * 1024 + ks * 16);
;         s[0] = __builtin_amdgcn_mfma_f32_32x32x16_bf16(a, b0, s[0], 0, 0, 0);
;         s[1] = __builtin_amdgcn_mfma_f32_32x32x16_bf16(a, b1, s[1], 0, 0, 0);
;     }
.LBB0_597:
	v_lshrrev_b32_e32 v2, 1, v36
	v_and_b32_e32 v38, 31, v36
	v_and_b32_e32 v37, 0x60, v2
	s_lshl_b32 s2, s16, 8
	v_ashrrev_i32_e32 v0, 2, v36
	s_ashr_i32 s3, s2, 31
	v_and_b32_e32 v39, 0xffffffc0, v0
	v_add3_u32 v0, s6, v37, v38
	v_ashrrev_i32_e32 v1, 31, v0
	s_lshl_b64 s[2:3], s[2:3], 1
	v_lshlrev_b64 v[0:1], 11, v[0:1]
	v_and_b32_e32 v2, 16, v2
	s_add_u32 s8, s47, s2
	v_or_b32_e32 v0, v0, v2
	s_addc_u32 s9, s48, s3
	v_lshl_add_u64 v[32:33], s[8:9], 0, v[0:1]
	v_add3_u32 v0, s6, v39, v38
	v_ashrrev_i32_e32 v1, 31, v0
	v_lshlrev_b64 v[0:1], 11, v[0:1]
	s_add_u32 s2, s38, s2
	v_or_b32_e32 v0, v0, v2
	s_addc_u32 s3, s39, s3
	v_mov_b32_e32 v16, 0
	v_lshl_add_u64 v[34:35], s[2:3], 0, v[0:1]
	s_mov_b64 s[40:41], 0
	v_mov_b32_e32 v17, v16
	v_mov_b32_e32 v18, v16
	v_mov_b32_e32 v19, v16
	v_mov_b32_e32 v20, v16
	v_mov_b32_e32 v21, v16
	v_mov_b32_e32 v22, v16
	v_mov_b32_e32 v23, v16
	v_mov_b32_e32 v24, v16
	v_mov_b32_e32 v25, v16
	v_mov_b32_e32 v26, v16
	v_mov_b32_e32 v27, v16
	v_mov_b32_e32 v28, v16
	v_mov_b32_e32 v29, v16
	v_mov_b32_e32 v30, v16
	v_mov_b32_e32 v31, v16
	v_mov_b32_e32 v0, v16
	v_mov_b32_e32 v1, v16
	v_mov_b32_e32 v2, v16
	v_mov_b32_e32 v3, v16
	v_mov_b32_e32 v4, v16
	v_mov_b32_e32 v5, v16
	v_mov_b32_e32 v6, v16
	v_mov_b32_e32 v7, v16
	v_mov_b32_e32 v8, v16
	v_mov_b32_e32 v9, v16
	v_mov_b32_e32 v10, v16
	v_mov_b32_e32 v11, v16
	v_mov_b32_e32 v12, v16
	v_mov_b32_e32 v13, v16
	v_mov_b32_e32 v14, v16
	v_mov_b32_e32 v15, v16
	s_mov_b32 s2, 0x7400000
	v_add_co_u32_e32 v54, vcc, s2, v34
	s_mov_b32 s2, 0x7410000
	s_nop 0
	v_addc_co_u32_e32 v55, vcc, 0, v35, vcc
	v_add_co_u32_e32 v56, vcc, s2, v34
	s_nop 1
	v_addc_co_u32_e32 v57, vcc, 0, v35, vcc

; __device__ __forceinline__ void ret_p_unit(const bf16_t* __restrict__ Q, const bf16_t* __restrict__ K, bf16_t* Pt, int b, int h, int ci, float lgf, float lgb) {
;     ...
;     const bf16_t* qp = Q + (size_t)(row0 + 32 * ib + l31) * 1024 + h * 256 + h2 * 8;
;     ...
;         const bf16x8 a = *(const bf16x8*)(qp + ks * 16);
	v_add_u32_e32 v58, s6, v37
	v_mov_b32_e32 v59, 0
	v_lshlrev_b64 v[58:59], 11, v[58:59]
	v_lshl_or_b32 v58, v38, 4, v58
	v_bfe_u32 v60, v36, 5, 1
	v_lshl_or_b32 v58, v60, 9, v58
	s_lshl_b32 s98, s16, 14
	s_add_u32 s98, s47, s98
	s_addc_u32 s99, s48, 0
	s_sub_u32 s98, s98, 64
	s_subb_u32 s99, s99, 0
	v_lshl_add_u64 v[58:59], s[98:99], 0, v[58:59]
	s_mov_b64 s[98:99], 0x1000
	v_lshl_add_u64 v[60:61], v[58:59], 0, s[98:99]
	v_lshl_add_u64 v[62:63], v[60:61], 0, s[98:99]
	v_lshl_add_u64 v[64:65], v[62:63], 0, s[98:99]

; __device__ __forceinline__ void ret_p_unit(const bf16_t* __restrict__ Q, const bf16_t* __restrict__ K, bf16_t* Pt, int b, int h, int ci, float lgf, float lgb) {
;     ...
; #pragma unroll 4
;     for (int ks = 0; ks < 16; ++ks) {
;         const bf16x8 a = *(const bf16x8*)(qp + ks * 16);
;         const bf16x8 b0 = *(const bf16x8*)(kp0 + ks * 16), b1 = *(const bf16x8*)(kp0 + 32 * 1024 + ks * 16);
;         s[0] = __builtin_amdgcn_mfma_f32_32x32x16_bf16(a, b0, s[0], 0, 0, 0);
;         s[1] = __builtin_amdgcn_mfma_f32_32x32x16_bf16(a, b1, s[1], 0, 0, 0);
;     }
	global_load_dwordx4 v[104:107], v[58:59], off
	global_load_dwordx4 v[108:111], v[54:55], off
	global_load_dwordx4 v[112:115], v[56:57], off
	global_load_dwordx4 v[116:119], v[58:59], off offset:1024
	global_load_dwordx4 v[120:123], v[54:55], off offset:32
	global_load_dwordx4 v[124:127], v[56:57], off offset:32
	global_load_dwordx4 v[128:131], v[58:59], off offset:2048
	global_load_dwordx4 v[132:135], v[54:55], off offset:64
	global_load_dwordx4 v[136:139], v[56:57], off offset:64
	global_load_dwordx4 v[140:143], v[58:59], off offset:3072
	global_load_dwordx4 v[144:147], v[54:55], off offset:96
	global_load_dwordx4 v[148:151], v[56:57], off offset:96
	global_load_dwordx4 v[152:155], v[60:61], off
	global_load_dwordx4 v[156:159], v[54:55], off offset:128
	global_load_dwordx4 v[160:163], v[56:57], off offset:128
	global_load_dwordx4 v[164:167], v[60:61], off offset:1024
	global_load_dwordx4 v[168:171], v[54:55], off offset:160
	global_load_dwordx4 v[172:175], v[56:57], off offset:160
	global_load_dwordx4 v[176:179], v[60:61], off offset:2048
	global_load_dwordx4 v[184:187], v[54:55], off offset:192
	global_load_dwordx4 v[188:191], v[56:57], off offset:192
	global_load_dwordx4 v[212:215], v[60:61], off offset:3072
	global_load_dwordx4 v[216:219], v[54:55], off offset:224
	global_load_dwordx4 v[220:223], v[56:57], off offset:224
	s_waitcnt vmcnt(22)
	v_mfma_f32_32x32x16_bf16 v[16:31], v[104:107], v[108:111], v[16:31]
	s_waitcnt vmcnt(21)
	v_mfma_f32_32x32x16_bf16 v[0:15], v[104:107], v[112:115], v[0:15]
	s_waitcnt vmcnt(19)
	v_mfma_f32_32x32x16_bf16 v[16:31], v[116:119], v[120:123], v[16:31]
	s_waitcnt vmcnt(18)
	v_mfma_f32_32x32x16_bf16 v[0:15], v[116:119], v[124:127], v[0:15]
	s_waitcnt vmcnt(16)
	v_mfma_f32_32x32x16_bf16 v[16:31], v[128:131], v[132:135], v[16:31]
	s_waitcnt vmcnt(15)
	v_mfma_f32_32x32x16_bf16 v[0:15], v[128:131], v[136:139], v[0:15]
	s_waitcnt vmcnt(13)
	v_mfma_f32_32x32x16_bf16 v[16:31], v[140:143], v[144:147], v[16:31]
	s_waitcnt vmcnt(12)
	v_mfma_f32_32x32x16_bf16 v[0:15], v[140:143], v[148:151], v[0:15]
	global_load_dwordx4 v[104:107], v[62:63], off
	global_load_dwordx4 v[108:111], v[54:55], off offset:256
	global_load_dwordx4 v[112:115], v[56:57], off offset:256
	global_load_dwordx4 v[116:119], v[62:63], off offset:1024
	global_load_dwordx4 v[120:123], v[54:55], off offset:288
	global_load_dwordx4 v[124:127], v[56:57], off offset:288
	global_load_dwordx4 v[128:131], v[62:63], off offset:2048
	global_load_dwordx4 v[132:135], v[54:55], off offset:320
	global_load_dwordx4 v[136:139], v[56:57], off offset:320
	global_load_dwordx4 v[140:143], v[62:63], off offset:3072
	global_load_dwordx4 v[144:147], v[54:55], off offset:352
	global_load_dwordx4 v[148:151], v[56:57], off offset:352
	s_waitcnt vmcnt(22)
	v_mfma_f32_32x32x16_bf16 v[16:31], v[152:155], v[156:159], v[16:31]
	s_waitcnt vmcnt(21)
	v_mfma_f32_32x32x16_bf16 v[0:15], v[152:155], v[160:163], v[0:15]
	s_waitcnt vmcnt(19)
	v_mfma_f32_32x32x16_bf16 v[16:31], v[164:167], v[168:171], v[16:31]
	s_waitcnt vmcnt(18)
	v_mfma_f32_32x32x16_bf16 v[0:15], v[164:167], v[172:175], v[0:15]
	s_waitcnt vmcnt(16)
	v_mfma_f32_32x32x16_bf16 v[16:31], v[176:179], v[184:187], v[16:31]
	s_waitcnt vmcnt(15)
	v_mfma_f32_32x32x16_bf16 v[0:15], v[176:179], v[188:191], v[0:15]
	s_waitcnt vmcnt(13)
	v_mfma_f32_32x32x16_bf16 v[16:31], v[212:215], v[216:219], v[16:31]
	s_waitcnt vmcnt(12)
	v_mfma_f32_32x32x16_bf16 v[0:15], v[212:215], v[220:223], v[0:15]
	global_load_dwordx4 v[152:155], v[64:65], off
	global_load_dwordx4 v[156:159], v[54:55], off offset:384
	global_load_dwordx4 v[160:163], v[56:57], off offset:384
	global_load_dwordx4 v[164:167], v[64:65], off offset:1024
	global_load_dwordx4 v[168:171], v[54:55], off offset:416
	global_load_dwordx4 v[172:175], v[56:57], off offset:416
	global_load_dwordx4 v[176:179], v[64:65], off offset:2048
	global_load_dwordx4 v[184:187], v[54:55], off offset:448
	global_load_dwordx4 v[188:191], v[56:57], off offset:448
	global_load_dwordx4 v[212:215], v[64:65], off offset:3072
	global_load_dwordx4 v[216:219], v[54:55], off offset:480
	global_load_dwordx4 v[220:223], v[56:57], off offset:480
	s_waitcnt vmcnt(22)
	v_mfma_f32_32x32x16_bf16 v[16:31], v[104:107], v[108:111], v[16:31]
	s_waitcnt vmcnt(21)
	v_mfma_f32_32x32x16_bf16 v[0:15], v[104:107], v[112:115], v[0:15]
	s_waitcnt vmcnt(19)
	v_mfma_f32_32x32x16_bf16 v[16:31], v[116:119], v[120:123], v[16:31]
	s_waitcnt vmcnt(18)
	v_mfma_f32_32x32x16_bf16 v[0:15], v[116:119], v[124:127], v[0:15]
	s_waitcnt vmcnt(16)
	v_mfma_f32_32x32x16_bf16 v[16:31], v[128:131], v[132:135], v[16:31]
	s_waitcnt vmcnt(15)
	v_mfma_f32_32x32x16_bf16 v[0:15], v[128:131], v[136:139], v[0:15]
	s_waitcnt vmcnt(13)
	v_mfma_f32_32x32x16_bf16 v[16:31], v[140:143], v[144:147], v[16:31]
	s_waitcnt vmcnt(12)
	v_mfma_f32_32x32x16_bf16 v[0:15], v[140:143], v[148:151], v[0:15]
	s_waitcnt vmcnt(10)
	v_mfma_f32_32x32x16_bf16 v[16:31], v[152:155], v[156:159], v[16:31]
	s_waitcnt vmcnt(9)
	v_mfma_f32_32x32x16_bf16 v[0:15], v[152:155], v[160:163], v[0:15]
	s_waitcnt vmcnt(7)
	v_mfma_f32_32x32x16_bf16 v[16:31], v[164:167], v[168:171], v[16:31]
	s_waitcnt vmcnt(6)
	v_mfma_f32_32x32x16_bf16 v[0:15], v[164:167], v[172:175], v[0:15]
	s_waitcnt vmcnt(4)
	v_mfma_f32_32x32x16_bf16 v[16:31], v[176:179], v[184:187], v[16:31]
	s_waitcnt vmcnt(3)
	v_mfma_f32_32x32x16_bf16 v[0:15], v[176:179], v[188:191], v[0:15]
	s_waitcnt vmcnt(1)
	v_mfma_f32_32x32x16_bf16 v[16:31], v[212:215], v[216:219], v[16:31]
	s_waitcnt vmcnt(0)
	v_mfma_f32_32x32x16_bf16 v[0:15], v[212:215], v[220:223], v[0:15]
	s_movk_i32 s40, 0x200
	s_mov_b32 s41, 0

; __device__ __forceinline__ unsigned cvt_pk_bf16(float lo, float hi) { unsigned r; asm volatile("v_cvt_pk_bf16_f32 %0, %1, %2" : "=v"(r) : "v"(lo), "v"(hi)); return r; }
; __device__ __forceinline__ int crow(int r, int h) { return (r & 3) + 8 * (r >> 2) + 4 * h; }
; __device__ __forceinline__ void ret_p_unit(const bf16_t* __restrict__ Q, const bf16_t* __restrict__ K, bf16_t* Pt, int b, int h, int ci, float lgf, float lgb) {
;     ...
; #pragma unroll
;     for (int jb = 0; jb < 2; ++jb)
; #pragma unroll
;         for (int r = 0; r < 16; ++r) {
;             const int i = 32 * ib + crow(r, h2), j = 64 * jh + 32 * jb + l31, df = i - j;
;             const float v = s[jb][r];
;             const float vf = df >= 0 ? v * __builtin_amdgcn_exp2f((float)df * lgf) : 0.f;
;             const float vb = df < 0 ? v * __builtin_amdgcn_exp2f((float)(-df) * lgb) : 0.f;
;             pf[i * 128 + j] = (bf16_t)(cvt_pk_bf16(vf, vf) & 0xffffu);
;             pb[i * 128 + j] = (bf16_t)(cvt_pk_bf16(vb, vb) & 0xffffu);
;         }
	v_lshrrev_b32_e32 v32, 3, v36
	v_or_b32_e32 v82, v39, v38
	v_and_or_b32 v83, v32, 4, v37
	v_sub_u32_e32 v32, v83, v82
	v_cvt_f32_u32_e32 v33, v32
	v_cmp_lt_i32_e32 vcc, -1, v32
	s_lshl_b32 s2, s5, 2
	s_add_i32 s5, s16, s2
	v_mul_f32_e32 v33, v81, v33
	v_exp_f32_e32 v33, v33
	s_mul_i32 s6, s5, 18
	s_ashr_i32 s7, s4, 31
	s_mul_hi_i32 s3, s5, 18
	v_mul_f32_e32 v33, v33, v16
	v_cndmask_b32_e32 v33, 0, v33, vcc
	v_cmp_gt_i32_e32 vcc, 0, v32
	v_sub_u32_e32 v32, 0, v32
	v_cvt_f32_u32_e32 v32, v32
	s_add_u32 s2, s6, s4
	s_addc_u32 s3, s3, s7
	s_lshl_b64 s[2:3], s[2:3], 15
	v_mul_f32_e32 v32, v80, v32
	v_exp_f32_e32 v32, v32
	s_add_u32 s16, s45, s2
	s_addc_u32 s17, s46, s3
	s_add_i32 s5, s5, 32
	s_addk_i32 s6, 0x240
	s_mul_hi_i32 s3, s5, 18
	s_add_u32 s2, s6, s4
	s_addc_u32 s3, s3, s7
	v_mul_f32_e32 v16, v32, v16
	v_lshl_add_u32 v32, v83, 7, v82
	s_lshl_b64 s[2:3], s[2:3], 15
	v_cvt_pk_bf16_f32 v36, v33, v33
	v_ashrrev_i32_e32 v33, 31, v32
	s_add_u32 s40, s45, s2
	v_lshlrev_b64 v[34:35], 1, v[32:33]
	s_addc_u32 s41, s46, s3
	v_cndmask_b32_e32 v16, 0, v16, vcc
	v_lshl_add_u64 v[32:33], s[16:17], 0, v[34:35]
	global_store_short v[32:33], v36, off
	v_cvt_pk_bf16_f32 v16, v16, v16
	v_lshl_add_u64 v[34:35], s[40:41], 0, v[34:35]
	v_or_b32_e32 v84, 1, v83
	global_store_short v[34:35], v16, off
	v_sub_u32_e32 v16, v84, v82
	v_cvt_f32_u32_e32 v36, v16
	v_cmp_lt_i32_e32 vcc, -1, v16
	v_or_b32_e32 v85, 2, v83
	v_or_b32_e32 v86, 3, v83
	v_mul_f32_e32 v36, v81, v36
	v_exp_f32_e32 v36, v36
	v_or_b32_e32 v87, 8, v83
	v_or_b32_e32 v88, 9, v83
	v_or_b32_e32 v89, 10, v83
	v_mul_f32_e32 v36, v36, v17
	v_cndmask_b32_e32 v36, 0, v36, vcc
	v_cmp_gt_i32_e32 vcc, 0, v16
	v_sub_u32_e32 v16, 0, v16
	v_cvt_f32_u32_e32 v16, v16
	v_cvt_pk_bf16_f32 v39, v36, v36
	v_or_b32_e32 v90, 11, v83
	v_or_b32_e32 v91, 16, v83
	v_mul_f32_e32 v16, v80, v16
	v_exp_f32_e32 v16, v16
	v_or_b32_e32 v92, 17, v83
	v_or_b32_e32 v93, 18, v83
	v_or_b32_e32 v94, 19, v83
	v_mul_f32_e32 v16, v16, v17
	v_cndmask_b32_e32 v38, 0, v16, vcc
	v_lshl_add_u32 v16, v84, 7, v82
	v_ashrrev_i32_e32 v17, 31, v16
	v_lshlrev_b64 v[36:37], 1, v[16:17]
	v_lshl_add_u64 v[16:17], s[16:17], 0, v[36:37]
	global_store_short v[16:17], v39, off
	v_cvt_pk_bf16_f32 v38, v38, v38
	v_lshl_add_u64 v[36:37], s[40:41], 0, v[36:37]
	global_store_short v[36:37], v38, off
	v_sub_u32_e32 v38, v85, v82
	v_cvt_f32_u32_e32 v39, v38
	v_cmp_lt_i32_e32 vcc, -1, v38
	v_or_b32_e32 v95, 24, v83
	v_or_b32_e32 v96, 25, v83
	v_mul_f32_e32 v39, v81, v39
	v_exp_f32_e32 v39, v39
	v_or_b32_e32 v97, 26, v83
	v_or_b32_e32 v98, 27, v83
	s_add_i32 s42, s42, s22
	v_mul_f32_e32 v39, v39, v18
	v_cndmask_b32_e32 v39, 0, v39, vcc
	v_cmp_gt_i32_e32 vcc, 0, v38
	v_sub_u32_e32 v38, 0, v38
	v_cvt_f32_u32_e32 v38, v38
	v_cvt_pk_bf16_f32 v42, v39, v39
	s_cmpk_lt_i32 s42, 0x240
	v_mul_f32_e32 v38, v80, v38
	v_exp_f32_e32 v38, v38
	s_nop 0
	v_mul_f32_e32 v18, v38, v18
	v_lshl_add_u32 v38, v85, 7, v82
	v_ashrrev_i32_e32 v39, 31, v38
	v_lshlrev_b64 v[40:41], 1, v[38:39]
	v_cndmask_b32_e32 v18, 0, v18, vcc
	v_lshl_add_u64 v[38:39], s[16:17], 0, v[40:41]
	global_store_short v[38:39], v42, off
	v_cvt_pk_bf16_f32 v18, v18, v18
	v_lshl_add_u64 v[40:41], s[40:41], 0, v[40:41]
	global_store_short v[40:41], v18, off
	v_sub_u32_e32 v18, v86, v82
	v_cvt_f32_u32_e32 v42, v18
	v_cmp_lt_i32_e32 vcc, -1, v18
	v_mul_f32_e32 v42, v81, v42
	v_exp_f32_e32 v42, v42
	s_nop 0
	v_mul_f32_e32 v42, v42, v19
	v_cndmask_b32_e32 v42, 0, v42, vcc
	v_cmp_gt_i32_e32 vcc, 0, v18
	v_sub_u32_e32 v18, 0, v18
	v_cvt_f32_u32_e32 v18, v18
	v_cvt_pk_bf16_f32 v45, v42, v42
	v_mul_f32_e32 v18, v80, v18
	v_exp_f32_e32 v18, v18
	s_nop 0
	v_mul_f32_e32 v18, v18, v19
	v_cndmask_b32_e32 v44, 0, v18, vcc
	v_lshl_add_u32 v18, v86, 7, v82
	v_ashrrev_i32_e32 v19, 31, v18
	v_lshlrev_b64 v[42:43], 1, v[18:19]
	v_lshl_add_u64 v[18:19], s[16:17], 0, v[42:43]
	global_store_short v[18:19], v45, off
	v_cvt_pk_bf16_f32 v44, v44, v44
	v_lshl_add_u64 v[42:43], s[40:41], 0, v[42:43]
	global_store_short v[42:43], v44, off
	v_sub_u32_e32 v44, v87, v82
	v_cvt_f32_u32_e32 v45, v44
	v_cmp_lt_i32_e32 vcc, -1, v44
	v_mul_f32_e32 v45, v81, v45
	v_exp_f32_e32 v45, v45
	s_nop 0
	v_mul_f32_e32 v45, v45, v20
	v_cndmask_b32_e32 v45, 0, v45, vcc
	v_cmp_gt_i32_e32 vcc, 0, v44
	v_sub_u32_e32 v44, 0, v44
	v_cvt_f32_u32_e32 v44, v44
	v_cvt_pk_bf16_f32 v48, v45, v45
	v_mul_f32_e32 v44, v80, v44
	v_exp_f32_e32 v44, v44
	s_nop 0
	v_mul_f32_e32 v20, v44, v20
	v_lshl_add_u32 v44, v87, 7, v82
	v_ashrrev_i32_e32 v45, 31, v44
	v_lshlrev_b64 v[46:47], 1, v[44:45]
	v_cndmask_b32_e32 v20, 0, v20, vcc
	v_lshl_add_u64 v[44:45], s[16:17], 0, v[46:47]
	global_store_short v[44:45], v48, off
	v_cvt_pk_bf16_f32 v20, v20, v20
	v_lshl_add_u64 v[46:47], s[40:41], 0, v[46:47]
	global_store_short v[46:47], v20, off
	v_sub_u32_e32 v20, v88, v82
	v_cvt_f32_u32_e32 v48, v20
	v_cmp_lt_i32_e32 vcc, -1, v20
	v_mul_f32_e32 v48, v81, v48
	v_exp_f32_e32 v48, v48
	s_nop 0
	v_mul_f32_e32 v48, v48, v21
	v_cndmask_b32_e32 v48, 0, v48, vcc
	v_cmp_gt_i32_e32 vcc, 0, v20
	v_sub_u32_e32 v20, 0, v20
	v_cvt_f32_u32_e32 v20, v20
	v_cvt_pk_bf16_f32 v51, v48, v48
	v_mul_f32_e32 v20, v80, v20
	v_exp_f32_e32 v20, v20
	s_nop 0
	v_mul_f32_e32 v20, v20, v21
	v_cndmask_b32_e32 v50, 0, v20, vcc
	v_lshl_add_u32 v20, v88, 7, v82
	v_ashrrev_i32_e32 v21, 31, v20
	v_lshlrev_b64 v[48:49], 1, v[20:21]
	v_lshl_add_u64 v[20:21], s[16:17], 0, v[48:49]
	global_store_short v[20:21], v51, off
	v_cvt_pk_bf16_f32 v50, v50, v50
	v_lshl_add_u64 v[48:49], s[40:41], 0, v[48:49]
	global_store_short v[48:49], v50, off
	v_sub_u32_e32 v50, v89, v82
	v_cvt_f32_u32_e32 v51, v50
	v_cmp_lt_i32_e32 vcc, -1, v50
; __device__ __forceinline__ unsigned cvt_pk_bf16(float lo, float hi) { unsigned r; asm volatile("v_cvt_pk_bf16_f32 %0, %1, %2" : "=v"(r) : "v"(lo), "v"(hi)); return r; }
; __device__ __forceinline__ int crow(int r, int h) { return (r & 3) + 8 * (r >> 2) + 4 * h; }
; __device__ __forceinline__ void ret_p_unit(const bf16_t* __restrict__ Q, const bf16_t* __restrict__ K, bf16_t* Pt, int b, int h, int ci, float lgf, float lgb) {
;     ...
; #pragma unroll
;     for (int jb = 0; jb < 2; ++jb)
; #pragma unroll
;         for (int r = 0; r < 16; ++r) {
;             const int i = 32 * ib + crow(r, h2), j = 64 * jh + 32 * jb + l31, df = i - j;
;             const float v = s[jb][r];
;             const float vf = df >= 0 ? v * __builtin_amdgcn_exp2f((float)df * lgf) : 0.f;
;             const float vb = df < 0 ? v * __builtin_amdgcn_exp2f((float)(-df) * lgb) : 0.f;
;             pf[i * 128 + j] = (bf16_t)(cvt_pk_bf16(vf, vf) & 0xffffu);
;             pb[i * 128 + j] = (bf16_t)(cvt_pk_bf16(vb, vb) & 0xffffu);
;         }
	v_mul_f32_e32 v51, v81, v51
	v_exp_f32_e32 v51, v51
	s_nop 0
	v_mul_f32_e32 v51, v51, v22
	v_cndmask_b32_e32 v51, 0, v51, vcc
	v_cmp_gt_i32_e32 vcc, 0, v50
	v_sub_u32_e32 v50, 0, v50
	v_cvt_f32_u32_e32 v50, v50
	v_cvt_pk_bf16_f32 v54, v51, v51
	v_mul_f32_e32 v50, v80, v50
	v_exp_f32_e32 v50, v50
	s_nop 0
	v_mul_f32_e32 v22, v50, v22
	v_lshl_add_u32 v50, v89, 7, v82
	v_ashrrev_i32_e32 v51, 31, v50
	v_lshlrev_b64 v[52:53], 1, v[50:51]
	v_cndmask_b32_e32 v22, 0, v22, vcc
	v_lshl_add_u64 v[50:51], s[16:17], 0, v[52:53]
	global_store_short v[50:51], v54, off
	v_cvt_pk_bf16_f32 v22, v22, v22
	v_lshl_add_u64 v[52:53], s[40:41], 0, v[52:53]
	global_store_short v[52:53], v22, off
	v_sub_u32_e32 v22, v90, v82
	v_cvt_f32_u32_e32 v54, v22
	v_cmp_lt_i32_e32 vcc, -1, v22
	v_mul_f32_e32 v54, v81, v54
	v_exp_f32_e32 v54, v54
	s_nop 0
	v_mul_f32_e32 v54, v54, v23
	v_cndmask_b32_e32 v54, 0, v54, vcc
	v_cmp_gt_i32_e32 vcc, 0, v22
	v_sub_u32_e32 v22, 0, v22
	v_cvt_f32_u32_e32 v22, v22
	v_cvt_pk_bf16_f32 v57, v54, v54
	v_mul_f32_e32 v22, v80, v22
	v_exp_f32_e32 v22, v22
	s_nop 0
	v_mul_f32_e32 v22, v22, v23
	v_cndmask_b32_e32 v56, 0, v22, vcc
	v_lshl_add_u32 v22, v90, 7, v82
	v_ashrrev_i32_e32 v23, 31, v22
	v_lshlrev_b64 v[54:55], 1, v[22:23]
	v_lshl_add_u64 v[22:23], s[16:17], 0, v[54:55]
	global_store_short v[22:23], v57, off
	v_cvt_pk_bf16_f32 v56, v56, v56
	v_lshl_add_u64 v[54:55], s[40:41], 0, v[54:55]
	global_store_short v[54:55], v56, off
	v_sub_u32_e32 v56, v91, v82
	v_cvt_f32_u32_e32 v57, v56
	v_cmp_lt_i32_e32 vcc, -1, v56
	v_mul_f32_e32 v57, v81, v57
	v_exp_f32_e32 v57, v57
	s_nop 0
	v_mul_f32_e32 v57, v57, v24
	v_cndmask_b32_e32 v57, 0, v57, vcc
	v_cmp_gt_i32_e32 vcc, 0, v56
	v_sub_u32_e32 v56, 0, v56
	v_cvt_f32_u32_e32 v56, v56
	v_cvt_pk_bf16_f32 v60, v57, v57
	v_mul_f32_e32 v56, v80, v56
	v_exp_f32_e32 v56, v56
	s_nop 0
	v_mul_f32_e32 v24, v56, v24
	v_lshl_add_u32 v56, v91, 7, v82
	v_ashrrev_i32_e32 v57, 31, v56
	v_lshlrev_b64 v[58:59], 1, v[56:57]
	v_cndmask_b32_e32 v24, 0, v24, vcc
	v_lshl_add_u64 v[56:57], s[16:17], 0, v[58:59]
	global_store_short v[56:57], v60, off
	v_cvt_pk_bf16_f32 v24, v24, v24
	v_lshl_add_u64 v[58:59], s[40:41], 0, v[58:59]
	global_store_short v[58:59], v24, off
	v_sub_u32_e32 v24, v92, v82
	v_cvt_f32_u32_e32 v60, v24
	v_cmp_lt_i32_e32 vcc, -1, v24
	v_mul_f32_e32 v60, v81, v60
	v_exp_f32_e32 v60, v60
	s_nop 0
	v_mul_f32_e32 v60, v60, v25
	v_cndmask_b32_e32 v60, 0, v60, vcc
	v_cmp_gt_i32_e32 vcc, 0, v24
	v_sub_u32_e32 v24, 0, v24
	v_cvt_f32_u32_e32 v24, v24
	v_cvt_pk_bf16_f32 v63, v60, v60
	v_mul_f32_e32 v24, v80, v24
	v_exp_f32_e32 v24, v24
	s_nop 0
	v_mul_f32_e32 v24, v24, v25
	v_cndmask_b32_e32 v62, 0, v24, vcc
	v_lshl_add_u32 v24, v92, 7, v82
	v_ashrrev_i32_e32 v25, 31, v24
	v_lshlrev_b64 v[60:61], 1, v[24:25]
	v_lshl_add_u64 v[24:25], s[16:17], 0, v[60:61]
	global_store_short v[24:25], v63, off
	v_cvt_pk_bf16_f32 v62, v62, v62
	v_lshl_add_u64 v[60:61], s[40:41], 0, v[60:61]
	global_store_short v[60:61], v62, off
	v_sub_u32_e32 v62, v93, v82
	v_cvt_f32_u32_e32 v63, v62
	v_cmp_lt_i32_e32 vcc, -1, v62
	v_mul_f32_e32 v63, v81, v63
	v_exp_f32_e32 v63, v63
	s_nop 0
	v_mul_f32_e32 v63, v63, v26
	v_cndmask_b32_e32 v63, 0, v63, vcc
	v_cmp_gt_i32_e32 vcc, 0, v62
	v_sub_u32_e32 v62, 0, v62
	v_cvt_f32_u32_e32 v62, v62
	v_cvt_pk_bf16_f32 v66, v63, v63
	v_mul_f32_e32 v62, v80, v62
	v_exp_f32_e32 v62, v62
	s_nop 0
	v_mul_f32_e32 v26, v62, v26
	v_lshl_add_u32 v62, v93, 7, v82
	v_ashrrev_i32_e32 v63, 31, v62
	v_lshlrev_b64 v[64:65], 1, v[62:63]
	v_cndmask_b32_e32 v26, 0, v26, vcc
	v_lshl_add_u64 v[62:63], s[16:17], 0, v[64:65]
	global_store_short v[62:63], v66, off
	v_cvt_pk_bf16_f32 v26, v26, v26
	v_lshl_add_u64 v[64:65], s[40:41], 0, v[64:65]
	global_store_short v[64:65], v26, off
	v_sub_u32_e32 v26, v94, v82
	v_cvt_f32_u32_e32 v66, v26
	v_cmp_lt_i32_e32 vcc, -1, v26
	v_mul_f32_e32 v66, v81, v66
	v_exp_f32_e32 v66, v66
	s_nop 0
	v_mul_f32_e32 v66, v66, v27
	v_cndmask_b32_e32 v66, 0, v66, vcc
	v_cmp_gt_i32_e32 vcc, 0, v26
	v_sub_u32_e32 v26, 0, v26
	v_cvt_f32_u32_e32 v26, v26
	v_cvt_pk_bf16_f32 v69, v66, v66
	v_mul_f32_e32 v26, v80, v26
	v_exp_f32_e32 v26, v26
	s_nop 0
	v_mul_f32_e32 v26, v26, v27
	v_cndmask_b32_e32 v68, 0, v26, vcc
	v_lshl_add_u32 v26, v94, 7, v82
	v_ashrrev_i32_e32 v27, 31, v26
	v_lshlrev_b64 v[66:67], 1, v[26:27]
	v_lshl_add_u64 v[26:27], s[16:17], 0, v[66:67]
	global_store_short v[26:27], v69, off
	v_cvt_pk_bf16_f32 v68, v68, v68
	v_lshl_add_u64 v[66:67], s[40:41], 0, v[66:67]
	global_store_short v[66:67], v68, off
	v_sub_u32_e32 v68, v95, v82
	v_cvt_f32_u32_e32 v69, v68
	v_cmp_lt_i32_e32 vcc, -1, v68
	v_mul_f32_e32 v69, v81, v69
	v_exp_f32_e32 v69, v69
	s_nop 0
	v_mul_f32_e32 v69, v69, v28
	v_cndmask_b32_e32 v69, 0, v69, vcc
	v_cmp_gt_i32_e32 vcc, 0, v68
	v_sub_u32_e32 v68, 0, v68
	v_cvt_f32_u32_e32 v68, v68
	v_cvt_pk_bf16_f32 v72, v69, v69
	v_mul_f32_e32 v68, v80, v68
	v_exp_f32_e32 v68, v68
	s_nop 0
	v_mul_f32_e32 v28, v68, v28
	v_lshl_add_u32 v68, v95, 7, v82
	v_ashrrev_i32_e32 v69, 31, v68
	v_lshlrev_b64 v[70:71], 1, v[68:69]
	v_cndmask_b32_e32 v28, 0, v28, vcc
	v_lshl_add_u64 v[68:69], s[16:17], 0, v[70:71]
	global_store_short v[68:69], v72, off
	v_cvt_pk_bf16_f32 v28, v28, v28
	v_lshl_add_u64 v[70:71], s[40:41], 0, v[70:71]
	global_store_short v[70:71], v28, off
	v_sub_u32_e32 v28, v96, v82
	v_cvt_f32_u32_e32 v72, v28
	v_cmp_lt_i32_e32 vcc, -1, v28
	v_mul_f32_e32 v72, v81, v72
	v_exp_f32_e32 v72, v72
	s_nop 0
	v_mul_f32_e32 v72, v72, v29
	v_cndmask_b32_e32 v72, 0, v72, vcc
	v_cmp_gt_i32_e32 vcc, 0, v28
	v_sub_u32_e32 v28, 0, v28
	v_cvt_f32_u32_e32 v28, v28
	v_cvt_pk_bf16_f32 v75, v72, v72
; __device__ __forceinline__ unsigned cvt_pk_bf16(float lo, float hi) { unsigned r; asm volatile("v_cvt_pk_bf16_f32 %0, %1, %2" : "=v"(r) : "v"(lo), "v"(hi)); return r; }
; __device__ __forceinline__ int crow(int r, int h) { return (r & 3) + 8 * (r >> 2) + 4 * h; }
; __device__ __forceinline__ void ret_p_unit(const bf16_t* __restrict__ Q, const bf16_t* __restrict__ K, bf16_t* Pt, int b, int h, int ci, float lgf, float lgb) {
;     ...
; #pragma unroll
;     for (int jb = 0; jb < 2; ++jb)
; #pragma unroll
;         for (int r = 0; r < 16; ++r) {
;             const int i = 32 * ib + crow(r, h2), j = 64 * jh + 32 * jb + l31, df = i - j;
;             const float v = s[jb][r];
;             const float vf = df >= 0 ? v * __builtin_amdgcn_exp2f((float)df * lgf) : 0.f;
;             const float vb = df < 0 ? v * __builtin_amdgcn_exp2f((float)(-df) * lgb) : 0.f;
;             pf[i * 128 + j] = (bf16_t)(cvt_pk_bf16(vf, vf) & 0xffffu);
;             pb[i * 128 + j] = (bf16_t)(cvt_pk_bf16(vb, vb) & 0xffffu);
;         }
	v_mul_f32_e32 v28, v80, v28
	v_exp_f32_e32 v28, v28
	s_nop 0
	v_mul_f32_e32 v28, v28, v29
	v_cndmask_b32_e32 v74, 0, v28, vcc
	v_lshl_add_u32 v28, v96, 7, v82
	v_ashrrev_i32_e32 v29, 31, v28
	v_lshlrev_b64 v[72:73], 1, v[28:29]
	v_lshl_add_u64 v[28:29], s[16:17], 0, v[72:73]
	global_store_short v[28:29], v75, off
	v_cvt_pk_bf16_f32 v74, v74, v74
	v_lshl_add_u64 v[72:73], s[40:41], 0, v[72:73]
	global_store_short v[72:73], v74, off
	v_sub_u32_e32 v74, v97, v82
	v_cvt_f32_u32_e32 v75, v74
	v_cmp_lt_i32_e32 vcc, -1, v74
	v_mul_f32_e32 v75, v81, v75
	v_exp_f32_e32 v75, v75
	s_nop 0
	v_mul_f32_e32 v75, v75, v30
	v_cndmask_b32_e32 v75, 0, v75, vcc
	v_cmp_gt_i32_e32 vcc, 0, v74
	v_sub_u32_e32 v74, 0, v74
	v_cvt_f32_u32_e32 v74, v74
	v_cvt_pk_bf16_f32 v78, v75, v75
	v_mul_f32_e32 v74, v80, v74
	v_exp_f32_e32 v74, v74
	s_nop 0
	v_mul_f32_e32 v30, v74, v30
	v_lshl_add_u32 v74, v97, 7, v82
	v_ashrrev_i32_e32 v75, 31, v74
	v_lshlrev_b64 v[76:77], 1, v[74:75]
	v_cndmask_b32_e32 v30, 0, v30, vcc
	v_lshl_add_u64 v[74:75], s[16:17], 0, v[76:77]
	global_store_short v[74:75], v78, off
	v_cvt_pk_bf16_f32 v30, v30, v30
	v_lshl_add_u64 v[76:77], s[40:41], 0, v[76:77]
	global_store_short v[76:77], v30, off
	v_sub_u32_e32 v30, v98, v82
	v_cvt_f32_u32_e32 v78, v30
	v_cmp_lt_i32_e32 vcc, -1, v30
	v_mul_f32_e32 v78, v81, v78
	v_exp_f32_e32 v78, v78
	s_nop 0
	v_mul_f32_e32 v78, v78, v31
	v_cndmask_b32_e32 v78, 0, v78, vcc
	v_cmp_gt_i32_e32 vcc, 0, v30
	v_sub_u32_e32 v30, 0, v30
	v_cvt_f32_u32_e32 v30, v30
	v_cvt_pk_bf16_f32 v100, v78, v78
	v_mul_f32_e32 v30, v80, v30
	v_exp_f32_e32 v30, v30
	s_nop 0
	v_mul_f32_e32 v30, v30, v31
	v_cndmask_b32_e32 v99, 0, v30, vcc
	v_lshl_add_u32 v30, v98, 7, v82
	v_ashrrev_i32_e32 v31, 31, v30
	v_lshlrev_b64 v[78:79], 1, v[30:31]
	v_lshl_add_u64 v[30:31], s[16:17], 0, v[78:79]
	v_or_b32_e32 v82, 32, v82
	global_store_short v[30:31], v100, off
	v_cvt_pk_bf16_f32 v99, v99, v99
	v_lshl_add_u64 v[78:79], s[40:41], 0, v[78:79]
	v_sub_u32_e32 v83, v83, v82
	global_store_short v[78:79], v99, off
	v_cvt_f32_u32_e32 v99, v83
	v_cmp_lt_i32_e32 vcc, -1, v83
	v_mul_f32_e32 v99, v81, v99
	v_exp_f32_e32 v99, v99
	s_nop 0
	v_mul_f32_e32 v99, v99, v0
	v_cndmask_b32_e32 v99, 0, v99, vcc
	v_cmp_gt_i32_e32 vcc, 0, v83
	v_sub_u32_e32 v83, 0, v83
	v_cvt_f32_u32_e32 v83, v83
	v_mul_f32_e32 v83, v80, v83
	v_exp_f32_e32 v83, v83
	s_nop 0
	v_mul_f32_e32 v0, v83, v0
	v_cndmask_b32_e32 v0, 0, v0, vcc
	v_cvt_pk_bf16_f32 v83, v99, v99
	global_store_short v[32:33], v83, off offset:64
	v_cvt_pk_bf16_f32 v0, v0, v0
	global_store_short v[34:35], v0, off offset:64
	v_sub_u32_e32 v0, v84, v82
	v_cvt_f32_u32_e32 v32, v0
	v_cmp_lt_i32_e32 vcc, -1, v0
	v_mul_f32_e32 v32, v81, v32
	v_exp_f32_e32 v32, v32
	s_nop 0
	v_mul_f32_e32 v32, v32, v1
	v_cndmask_b32_e32 v32, 0, v32, vcc
	v_cmp_gt_i32_e32 vcc, 0, v0
	v_sub_u32_e32 v0, 0, v0
	v_cvt_f32_u32_e32 v0, v0
	v_mul_f32_e32 v0, v80, v0
	v_exp_f32_e32 v0, v0
	s_nop 0
	v_mul_f32_e32 v0, v0, v1
	v_cndmask_b32_e32 v0, 0, v0, vcc
	v_cvt_pk_bf16_f32 v1, v32, v32
	global_store_short v[16:17], v1, off offset:64
	v_cvt_pk_bf16_f32 v0, v0, v0
	global_store_short v[36:37], v0, off offset:64
	v_sub_u32_e32 v0, v85, v82
	v_cvt_f32_u32_e32 v1, v0
	v_cmp_lt_i32_e32 vcc, -1, v0
	v_mul_f32_e32 v1, v81, v1
	v_exp_f32_e32 v1, v1
	s_nop 0
	v_mul_f32_e32 v1, v1, v2
	v_cndmask_b32_e32 v1, 0, v1, vcc
	v_cmp_gt_i32_e32 vcc, 0, v0
	v_sub_u32_e32 v0, 0, v0
	v_cvt_f32_u32_e32 v0, v0
	v_cvt_pk_bf16_f32 v1, v1, v1
	global_store_short v[38:39], v1, off offset:64
	v_mul_f32_e32 v0, v80, v0
	v_exp_f32_e32 v0, v0
	s_nop 0
	v_mul_f32_e32 v0, v0, v2
	v_cndmask_b32_e32 v0, 0, v0, vcc
	v_cvt_pk_bf16_f32 v0, v0, v0
	global_store_short v[40:41], v0, off offset:64
	v_sub_u32_e32 v0, v86, v82
	v_cvt_f32_u32_e32 v1, v0
	v_cmp_lt_i32_e32 vcc, -1, v0
	v_mul_f32_e32 v1, v81, v1
	v_exp_f32_e32 v1, v1
	s_nop 0
	v_mul_f32_e32 v1, v1, v3
	v_cndmask_b32_e32 v1, 0, v1, vcc
	v_cmp_gt_i32_e32 vcc, 0, v0
	v_sub_u32_e32 v0, 0, v0
	v_cvt_f32_u32_e32 v0, v0
	v_cvt_pk_bf16_f32 v1, v1, v1
	global_store_short v[18:19], v1, off offset:64
	v_mul_f32_e32 v0, v80, v0
	v_exp_f32_e32 v0, v0
	s_nop 0
	v_mul_f32_e32 v0, v0, v3
	v_cndmask_b32_e32 v0, 0, v0, vcc
	v_cvt_pk_bf16_f32 v0, v0, v0
	global_store_short v[42:43], v0, off offset:64
	v_sub_u32_e32 v0, v87, v82
	v_cvt_f32_u32_e32 v1, v0
	v_cmp_lt_i32_e32 vcc, -1, v0
	v_mul_f32_e32 v1, v81, v1
	v_exp_f32_e32 v1, v1
	s_nop 0
	v_mul_f32_e32 v1, v1, v4
	v_cndmask_b32_e32 v1, 0, v1, vcc
	v_cmp_gt_i32_e32 vcc, 0, v0
	v_sub_u32_e32 v0, 0, v0
	v_cvt_f32_u32_e32 v0, v0
	v_cvt_pk_bf16_f32 v1, v1, v1
	global_store_short v[44:45], v1, off offset:64
	v_mul_f32_e32 v0, v80, v0
	v_exp_f32_e32 v0, v0
	s_nop 0
	v_mul_f32_e32 v0, v0, v4
	v_cndmask_b32_e32 v0, 0, v0, vcc
	v_cvt_pk_bf16_f32 v0, v0, v0
	global_store_short v[46:47], v0, off offset:64
	v_sub_u32_e32 v0, v88, v82
	v_cvt_f32_u32_e32 v1, v0
	v_cmp_lt_i32_e32 vcc, -1, v0
	v_mul_f32_e32 v1, v81, v1
	v_exp_f32_e32 v1, v1
	s_nop 0
	v_mul_f32_e32 v1, v1, v5
	v_cndmask_b32_e32 v1, 0, v1, vcc
	v_cmp_gt_i32_e32 vcc, 0, v0
	v_sub_u32_e32 v0, 0, v0
	v_cvt_f32_u32_e32 v0, v0
	v_cvt_pk_bf16_f32 v1, v1, v1
	global_store_short v[20:21], v1, off offset:64
	v_mul_f32_e32 v0, v80, v0
	v_exp_f32_e32 v0, v0
	s_nop 0
	v_mul_f32_e32 v0, v0, v5
	v_cndmask_b32_e32 v0, 0, v0, vcc
	v_cvt_pk_bf16_f32 v0, v0, v0
	global_store_short v[48:49], v0, off offset:64
	v_sub_u32_e32 v0, v89, v82
	v_cvt_f32_u32_e32 v1, v0
	v_cmp_lt_i32_e32 vcc, -1, v0
	v_mul_f32_e32 v1, v81, v1
; __device__ __forceinline__ unsigned cvt_pk_bf16(float lo, float hi) { unsigned r; asm volatile("v_cvt_pk_bf16_f32 %0, %1, %2" : "=v"(r) : "v"(lo), "v"(hi)); return r; }
; __device__ __forceinline__ int crow(int r, int h) { return (r & 3) + 8 * (r >> 2) + 4 * h; }
; __device__ __forceinline__ void ret_p_unit(const bf16_t* __restrict__ Q, const bf16_t* __restrict__ K, bf16_t* Pt, int b, int h, int ci, float lgf, float lgb) {
;     ...
; #pragma unroll
;     for (int jb = 0; jb < 2; ++jb)
; #pragma unroll
;         for (int r = 0; r < 16; ++r) {
;             const int i = 32 * ib + crow(r, h2), j = 64 * jh + 32 * jb + l31, df = i - j;
;             const float v = s[jb][r];
;             const float vf = df >= 0 ? v * __builtin_amdgcn_exp2f((float)df * lgf) : 0.f;
;             const float vb = df < 0 ? v * __builtin_amdgcn_exp2f((float)(-df) * lgb) : 0.f;
;             pf[i * 128 + j] = (bf16_t)(cvt_pk_bf16(vf, vf) & 0xffffu);
;             pb[i * 128 + j] = (bf16_t)(cvt_pk_bf16(vb, vb) & 0xffffu);
;         }
; __device__ __forceinline__ void ph_ret_p() {
;     ...
;     for (int u = bid; u < 576; u += G) { const int b = u / 72, r = u - b * 72, h = r / 18, ci = r - h * 18; ret_p_unit(Q, K, Pt, b, h, ci, lgt[h], lgt[4 + h]); }
	v_exp_f32_e32 v1, v1
	s_nop 0
	v_mul_f32_e32 v1, v1, v6
	v_cndmask_b32_e32 v1, 0, v1, vcc
	v_cmp_gt_i32_e32 vcc, 0, v0
	v_sub_u32_e32 v0, 0, v0
	v_cvt_f32_u32_e32 v0, v0
	v_cvt_pk_bf16_f32 v1, v1, v1
	global_store_short v[50:51], v1, off offset:64
	v_mul_f32_e32 v0, v80, v0
	v_exp_f32_e32 v0, v0
	s_nop 0
	v_mul_f32_e32 v0, v0, v6
	v_cndmask_b32_e32 v0, 0, v0, vcc
	v_cvt_pk_bf16_f32 v0, v0, v0
	global_store_short v[52:53], v0, off offset:64
	v_sub_u32_e32 v0, v90, v82
	v_cvt_f32_u32_e32 v1, v0
	v_cmp_lt_i32_e32 vcc, -1, v0
	v_mul_f32_e32 v1, v81, v1
	v_exp_f32_e32 v1, v1
	s_nop 0
	v_mul_f32_e32 v1, v1, v7
	v_cndmask_b32_e32 v1, 0, v1, vcc
	v_cmp_gt_i32_e32 vcc, 0, v0
	v_sub_u32_e32 v0, 0, v0
	v_cvt_f32_u32_e32 v0, v0
	v_cvt_pk_bf16_f32 v1, v1, v1
	global_store_short v[22:23], v1, off offset:64
	v_mul_f32_e32 v0, v80, v0
	v_exp_f32_e32 v0, v0
	s_nop 0
	v_mul_f32_e32 v0, v0, v7
	v_cndmask_b32_e32 v0, 0, v0, vcc
	v_cvt_pk_bf16_f32 v0, v0, v0
	global_store_short v[54:55], v0, off offset:64
	v_sub_u32_e32 v0, v91, v82
	v_cvt_f32_u32_e32 v1, v0
	v_cmp_lt_i32_e32 vcc, -1, v0
	v_mul_f32_e32 v1, v81, v1
	v_exp_f32_e32 v1, v1
	s_nop 0
	v_mul_f32_e32 v1, v1, v8
	v_cndmask_b32_e32 v1, 0, v1, vcc
	v_cmp_gt_i32_e32 vcc, 0, v0
	v_sub_u32_e32 v0, 0, v0
	v_cvt_f32_u32_e32 v0, v0
	v_cvt_pk_bf16_f32 v1, v1, v1
	global_store_short v[56:57], v1, off offset:64
	v_mul_f32_e32 v0, v80, v0
	v_exp_f32_e32 v0, v0
	s_nop 0
	v_mul_f32_e32 v0, v0, v8
	v_cndmask_b32_e32 v0, 0, v0, vcc
	v_cvt_pk_bf16_f32 v0, v0, v0
	global_store_short v[58:59], v0, off offset:64
	v_sub_u32_e32 v0, v92, v82
	v_cvt_f32_u32_e32 v1, v0
	v_cmp_lt_i32_e32 vcc, -1, v0
	v_mul_f32_e32 v1, v81, v1
	v_exp_f32_e32 v1, v1
	s_nop 0
	v_mul_f32_e32 v1, v1, v9
	v_cndmask_b32_e32 v1, 0, v1, vcc
	v_cmp_gt_i32_e32 vcc, 0, v0
	v_sub_u32_e32 v0, 0, v0
	v_cvt_f32_u32_e32 v0, v0
	v_cvt_pk_bf16_f32 v1, v1, v1
	global_store_short v[24:25], v1, off offset:64
	v_mul_f32_e32 v0, v80, v0
	v_exp_f32_e32 v0, v0
	s_nop 0
	v_mul_f32_e32 v0, v0, v9
	v_cndmask_b32_e32 v0, 0, v0, vcc
	v_cvt_pk_bf16_f32 v0, v0, v0
	global_store_short v[60:61], v0, off offset:64
	v_sub_u32_e32 v0, v93, v82
	v_cvt_f32_u32_e32 v1, v0
	v_cmp_lt_i32_e32 vcc, -1, v0
	v_mul_f32_e32 v1, v81, v1
	v_exp_f32_e32 v1, v1
	s_nop 0
	v_mul_f32_e32 v1, v1, v10
	v_cndmask_b32_e32 v1, 0, v1, vcc
	v_cmp_gt_i32_e32 vcc, 0, v0
	v_sub_u32_e32 v0, 0, v0
	v_cvt_f32_u32_e32 v0, v0
	v_cvt_pk_bf16_f32 v1, v1, v1
	global_store_short v[62:63], v1, off offset:64
	v_mul_f32_e32 v0, v80, v0
	v_exp_f32_e32 v0, v0
	s_nop 0
	v_mul_f32_e32 v0, v0, v10
	v_cndmask_b32_e32 v0, 0, v0, vcc
	v_cvt_pk_bf16_f32 v0, v0, v0
	global_store_short v[64:65], v0, off offset:64
	v_sub_u32_e32 v0, v94, v82
	v_cvt_f32_u32_e32 v1, v0
	v_cmp_lt_i32_e32 vcc, -1, v0
	v_mul_f32_e32 v1, v81, v1
	v_exp_f32_e32 v1, v1
	s_nop 0
	v_mul_f32_e32 v1, v1, v11
	v_cndmask_b32_e32 v1, 0, v1, vcc
	v_cmp_gt_i32_e32 vcc, 0, v0
	v_sub_u32_e32 v0, 0, v0
	v_cvt_f32_u32_e32 v0, v0
	v_cvt_pk_bf16_f32 v1, v1, v1
	global_store_short v[26:27], v1, off offset:64
	v_mul_f32_e32 v0, v80, v0
	v_exp_f32_e32 v0, v0
	s_nop 0
	v_mul_f32_e32 v0, v0, v11
	v_cndmask_b32_e32 v0, 0, v0, vcc
	v_cvt_pk_bf16_f32 v0, v0, v0
	global_store_short v[66:67], v0, off offset:64
	v_sub_u32_e32 v0, v95, v82
	v_cvt_f32_u32_e32 v1, v0
	v_cmp_lt_i32_e32 vcc, -1, v0
	v_mul_f32_e32 v1, v81, v1
	v_exp_f32_e32 v1, v1
	s_nop 0
	v_mul_f32_e32 v1, v1, v12
	v_cndmask_b32_e32 v1, 0, v1, vcc
	v_cmp_gt_i32_e32 vcc, 0, v0
	v_sub_u32_e32 v0, 0, v0
	v_cvt_f32_u32_e32 v0, v0
	v_cvt_pk_bf16_f32 v1, v1, v1
	global_store_short v[68:69], v1, off offset:64
	v_mul_f32_e32 v0, v80, v0
	v_exp_f32_e32 v0, v0
	s_nop 0
	v_mul_f32_e32 v0, v0, v12
	v_cndmask_b32_e32 v0, 0, v0, vcc
	v_cvt_pk_bf16_f32 v0, v0, v0
	global_store_short v[70:71], v0, off offset:64
	v_sub_u32_e32 v0, v96, v82
	v_cvt_f32_u32_e32 v1, v0
	v_cmp_lt_i32_e32 vcc, -1, v0
	v_mul_f32_e32 v1, v81, v1
	v_exp_f32_e32 v1, v1
	s_nop 0
	v_mul_f32_e32 v1, v1, v13
	v_cndmask_b32_e32 v1, 0, v1, vcc
	v_cmp_gt_i32_e32 vcc, 0, v0
	v_sub_u32_e32 v0, 0, v0
	v_cvt_f32_u32_e32 v0, v0
	v_cvt_pk_bf16_f32 v1, v1, v1
	global_store_short v[28:29], v1, off offset:64
	v_mul_f32_e32 v0, v80, v0
	v_exp_f32_e32 v0, v0
	s_nop 0
	v_mul_f32_e32 v0, v0, v13
	v_cndmask_b32_e32 v0, 0, v0, vcc
	v_cvt_pk_bf16_f32 v0, v0, v0
	global_store_short v[72:73], v0, off offset:64
	v_sub_u32_e32 v0, v97, v82
	v_cvt_f32_u32_e32 v1, v0
	v_cmp_lt_i32_e32 vcc, -1, v0
	v_mul_f32_e32 v1, v81, v1
	v_exp_f32_e32 v1, v1
	s_nop 0
	v_mul_f32_e32 v1, v1, v14
	v_cndmask_b32_e32 v1, 0, v1, vcc
	v_cmp_gt_i32_e32 vcc, 0, v0
	v_sub_u32_e32 v0, 0, v0
	v_cvt_f32_u32_e32 v0, v0
	v_cvt_pk_bf16_f32 v1, v1, v1
	global_store_short v[74:75], v1, off offset:64
	v_mul_f32_e32 v0, v80, v0
	v_exp_f32_e32 v0, v0
	s_nop 0
	v_mul_f32_e32 v0, v0, v14
	v_cndmask_b32_e32 v0, 0, v0, vcc
	v_cvt_pk_bf16_f32 v0, v0, v0
	global_store_short v[76:77], v0, off offset:64
	v_sub_u32_e32 v0, v98, v82
	v_cvt_f32_u32_e32 v1, v0
	v_cmp_lt_i32_e32 vcc, -1, v0
	v_mul_f32_e32 v1, v81, v1
	v_exp_f32_e32 v1, v1
	s_nop 0
	v_mul_f32_e32 v1, v1, v15
	v_cndmask_b32_e32 v1, 0, v1, vcc
	v_cmp_gt_i32_e32 vcc, 0, v0
	v_sub_u32_e32 v0, 0, v0
	v_cvt_f32_u32_e32 v0, v0
	v_cvt_pk_bf16_f32 v1, v1, v1
	global_store_short v[30:31], v1, off offset:64
	v_mul_f32_e32 v0, v80, v0
	v_exp_f32_e32 v0, v0
	s_nop 0
	v_mul_f32_e32 v0, v0, v15
	v_cndmask_b32_e32 v0, 0, v0, vcc
	v_cvt_pk_bf16_f32 v0, v0, v0
	global_store_short v[78:79], v0, off offset:64
	s_cbranch_scc1 .LBB0_593

;     __device__ __forceinline__ void operator()(const f32x4 (&acc)[2][2][4][2], const pg8::Unit& u, int wr, int wc, int fr, int fq) const {
;         const int row0 = u.pm * 256 + wr * 64 + fr;
;         bf16_t* base; int ld, colt; int kind;
;         if (MODE == 2) {
;             if (u.pn < 4) { base = (bf16_t*)R; ld = 1024; colt = u.pn * 256; kind = 1; }
;             else if (u.pn < 8) { base = (bf16_t*)(R + 36 * MiB); ld = 1024; colt = (u.pn - 4) * 256; kind = 2; }
;             else if (u.pn < 16) { base = (bf16_t*)(R + 72 * MiB); ld = 2048; colt = (u.pn - 8) * 256; kind = 0; }
;             else { base = (bf16_t*)(R + 144 * MiB); ld = 2048; colt = (u.pn - 16) * 256; kind = 3; }
;         } else {
;             const int sec = u.pn >> 2; base = (bf16_t*)(R + (size_t)sec * 36 * MiB); ld = 1024; colt = (u.pn & 3) * 256; kind = (MODE == 0 && sec < 2) ? 1 : 0;
;         }
;         const bool latent = u.pm < 64;
;         if (!latent && (kind == 1 || kind == 2)) kind = (kind == 2) ? 4 : 0;
;         const float ksc = 0.0625f;
; #pragma unroll
;         for (int ai = 0; ai < 2; ++ai)
; #pragma unroll
;             for (int m = 0; m < 4; ++m) {
;                 const int row = row0 + ai * 128 + m * 16;
;                 bf16_t* rowp = base + (size_t)row * ld + colt + wc * 32 + 8 * fq;
.LBB0_685:
	s_cmp_lt_i32 s38, 4
	s_cselect_b64 s[50:51], -1, 0
	s_mov_b64 s[98:99], s[50:51]
	s_lshl_b32 s100, s16, 19
	s_lshl_b32 s101, s38, 14
	s_add_u32 s100, s100, s101
	s_add_u32 s100, s18, s100
	s_addc_u32 s101, s19, 0
	v_and_b32_e32 v229, 15, v194
	v_lshlrev_b32_e32 v229, 4, v229
	v_bfe_u32 v230, v194, 4, 1
	v_lshl_add_u32 v229, v230, 9, v229
	v_bfe_u32 v230, v194, 5, 1
	v_lshl_add_u32 v229, v230, 10, v229
	v_bfe_u32 v230, v194, 6, 2
	v_lshl_add_u32 v229, v230, 11, v229
	v_bfe_u32 v230, v194, 8, 1
	v_lshl_add_u32 v229, v230, 17, v229
	v_mov_b32_e32 v231, 0
	v_mov_b32_e32 v235, 0
	v_mov_b32_e32 v234, 0x1f00
	v_cndmask_b32_e64 v234, 0, v234, s[98:99]

;     __device__ __forceinline__ void operator()(const f32x4 (&acc)[2][2][4][2], const pg8::Unit& u, int wr, int wc, int fr, int fq) const {
;     ...
;         if (MODE == 2) {
;             if (u.pn < 4) { base = (bf16_t*)R; ld = 1024; colt = u.pn * 256; kind = 1; }
;             else if (u.pn < 8) { base = (bf16_t*)(R + 36 * MiB); ld = 1024; colt = (u.pn - 4) * 256; kind = 2; }
;             else if (u.pn < 16) { base = (bf16_t*)(R + 72 * MiB); ld = 2048; colt = (u.pn - 8) * 256; kind = 0; }
;             else { base = (bf16_t*)(R + 144 * MiB); ld = 2048; colt = (u.pn - 16) * 256; kind = 3; }
	s_lshl_b32 s40, s38, 8
	s_and_b64 vcc, exec, s[50:51]
	s_cbranch_vccnz .LBB0_694
	s_cmp_gt_u32 s38, 7
	s_mov_b64 s[2:3], -1
	s_cbranch_scc0 .LBB0_692
	s_cmp_gt_u32 s38, 15
	s_cbranch_scc0 .LBB0_689
	s_add_i32 s4, s40, 0xfffff000
	s_mov_b64 s[2:3], 0

; __device__ __forceinline__ unsigned cvt_pk_bf16(float lo, float hi) { unsigned r; asm volatile("v_cvt_pk_bf16_f32 %0, %1, %2" : "=v"(r) : "v"(lo), "v"(hi)); return r; }
; __device__ __forceinline__ float silu_f(float v) { return v * __builtin_amdgcn_rcpf(1.f + __builtin_amdgcn_exp2f(-v * LOG2E)); }
;     __device__ __forceinline__ void operator()(const f32x4 (&acc)[2][2][4][2], const pg8::Unit& u, int wr, int wc, int fr, int fq) const {
;     ...
;                 const int row = row0 + ai * 128 + m * 16;
;                 bf16_t* rowp = base + (size_t)row * ld + colt + wc * 32 + 8 * fq;
;                 const int t = row & 2047, grow = t >> 6, gcol = t & 63;
; #pragma unroll
;                 for (int bj = 0; bj < 2; ++bj) {
;                     f32x4 v0 = acc[ai][bj][m][0], v1 = acc[ai][bj][m][1];
;                     if (kind == 1 || kind == 2) {
;                         f32x4 cs, sn;
;                         if (MODE == 0) { const int pos = (wc & 1) ? gcol : grow; const float* tp = tab + pos * 16 + 4 * fq; cs = *(const f32x4*)tp; sn = *(const f32x4*)(tp + 1024); }
;                         else { const int pos = bj ? gcol : grow; const float* tp = tab + 2048 + pos * 64 + 16 * wc + 4 * fq; cs = *(const f32x4*)tp; sn = *(const f32x4*)(tp + 4096); }
;                         const f32x4 o0 = v0 * cs - v1 * sn, o1 = v0 * sn + v1 * cs; v0 = o0; v1 = o1;
;                     }
;                     if (kind == 2 || kind == 4) { v0 = v0 * ksc; v1 = v1 * ksc; }
;                     if (kind == 3) {
; #pragma unroll
;                         for (int e = 0; e < 4; ++e) { v0[e] = silu_f(v0[e]); v1[e] = silu_f(v1[e]); }
;                     }
;                     u32x4 w; w.x = cvt_pk_bf16(v0[0], v0[1]); w.y = cvt_pk_bf16(v0[2], v0[3]); w.z = cvt_pk_bf16(v1[0], v1[1]); w.w = cvt_pk_bf16(v1[2], v1[3]);
;                     *(u32x4*)(rowp + bj * 128) = w;
.LBB0_702:
	s_ashr_i32 s41, s40, 31
	s_lshl_b64 s[2:3], s[40:41], 1
	s_add_u32 s2, s48, s2
	s_addc_u32 s3, s49, s3
	s_add_u32 s2, s2, s43
	v_or_b32_e32 v165, s4, v162
	s_addc_u32 s3, s3, 0
	v_lshl_add_u64 v[158:159], s[2:3], 0, v[180:181]
	v_mad_i64_i32 v[160:161], s[2:3], s66, v165, 0
	v_cvt_pk_bf16_f32 v124, v124, v125
	v_cvt_pk_bf16_f32 v125, v126, v127
	v_cvt_pk_bf16_f32 v126, v120, v121
	v_cndmask_b32_e64 v120, 0, 1, s[16:17]
	v_lshl_add_u64 v[160:161], v[160:161], 1, v[158:159]
	v_cmp_ne_u32_e64 s[38:39], 1, v120
	s_andn2_b64 vcc, exec, s[16:17]
	v_cvt_pk_bf16_f32 v127, v122, v123
	v_add_u32_e32 v230, 0x0, v229
	v_lshl_add_u64 v[232:233], s[100:101], 0, v[230:231]
	v_cndmask_b32_e64 v160, v160, v232, s[98:99]
	v_cndmask_b32_e64 v161, v161, v233, s[98:99]

; __device__ __forceinline__ unsigned cvt_pk_bf16(float lo, float hi) { unsigned r; asm volatile("v_cvt_pk_bf16_f32 %0, %1, %2" : "=v"(r) : "v"(lo), "v"(hi)); return r; }
; __device__ __forceinline__ float silu_f(float v) { return v * __builtin_amdgcn_rcpf(1.f + __builtin_amdgcn_exp2f(-v * LOG2E)); }
;     __device__ __forceinline__ void operator()(const f32x4 (&acc)[2][2][4][2], const pg8::Unit& u, int wr, int wc, int fr, int fq) const {
;     ...
;                     if (kind == 1 || kind == 2) {
;                         f32x4 cs, sn;
;                         if (MODE == 0) { const int pos = (wc & 1) ? gcol : grow; const float* tp = tab + pos * 16 + 4 * fq; cs = *(const f32x4*)tp; sn = *(const f32x4*)(tp + 1024); }
;                         else { const int pos = bj ? gcol : grow; const float* tp = tab + 2048 + pos * 64 + 16 * wc + 4 * fq; cs = *(const f32x4*)tp; sn = *(const f32x4*)(tp + 4096); }
;                         const f32x4 o0 = v0 * cs - v1 * sn, o1 = v0 * sn + v1 * cs; v0 = o0; v1 = o1;
;                     }
;                     if (kind == 2 || kind == 4) { v0 = v0 * ksc; v1 = v1 * ksc; }
;                     if (kind == 3) {
; #pragma unroll
;                         for (int e = 0; e < 4; ++e) { v0[e] = silu_f(v0[e]); v1[e] = silu_f(v1[e]); }
;                     }
;                     u32x4 w; w.x = cvt_pk_bf16(v0[0], v0[1]); w.y = cvt_pk_bf16(v0[2], v0[3]); w.z = cvt_pk_bf16(v1[0], v1[1]); w.w = cvt_pk_bf16(v1[2], v1[3]);
;                     *(u32x4*)(rowp + bj * 128) = w;
	global_store_dwordx4 v[160:161], v[124:127], off
	s_cbranch_vccz .LBB0_783
	s_cmp_gt_i32 s57, 3
	s_mov_b64 s[2:3], -1
	s_cbranch_scc0 .LBB0_784

; __device__ __forceinline__ unsigned cvt_pk_bf16(float lo, float hi) { unsigned r; asm volatile("v_cvt_pk_bf16_f32 %0, %1, %2" : "=v"(r) : "v"(lo), "v"(hi)); return r; }
;     __device__ __forceinline__ void operator()(const f32x4 (&acc)[2][2][4][2], const pg8::Unit& u, int wr, int wc, int fr, int fq) const {
;     ...
;                     u32x4 w; w.x = cvt_pk_bf16(v0[0], v0[1]); w.y = cvt_pk_bf16(v0[2], v0[3]); w.z = cvt_pk_bf16(v1[0], v1[1]); w.w = cvt_pk_bf16(v1[2], v1[3]);
;                     *(u32x4*)(rowp + bj * 128) = w;
.LBB0_707:
	s_and_b64 vcc, exec, s[38:39]
	v_cvt_pk_bf16_f32 v116, v116, v117
	v_cvt_pk_bf16_f32 v117, v118, v119
	v_cvt_pk_bf16_f32 v118, v112, v113
	v_cvt_pk_bf16_f32 v119, v114, v115
	v_lshl_add_u64 v[160:161], v[160:161], 0, v[234:235]

;     __device__ __forceinline__ void operator()(const f32x4 (&acc)[2][2][4][2], const pg8::Unit& u, int wr, int wc, int fr, int fq) const {
;     ...
;                     *(u32x4*)(rowp + bj * 128) = w;
	global_store_dwordx4 v[160:161], v[116:119], off offset:256
	s_cbranch_vccz .LBB0_786
	s_cmp_gt_i32 s57, 3
	s_mov_b64 s[2:3], -1
	s_cbranch_scc0 .LBB0_787

; __device__ __forceinline__ unsigned cvt_pk_bf16(float lo, float hi) { unsigned r; asm volatile("v_cvt_pk_bf16_f32 %0, %1, %2" : "=v"(r) : "v"(lo), "v"(hi)); return r; }
; __device__ __forceinline__ float silu_f(float v) { return v * __builtin_amdgcn_rcpf(1.f + __builtin_amdgcn_exp2f(-v * LOG2E)); }
;     __device__ __forceinline__ void operator()(const f32x4 (&acc)[2][2][4][2], const pg8::Unit& u, int wr, int wc, int fr, int fq) const {
;     ...
;                 const int row = row0 + ai * 128 + m * 16;
;                 bf16_t* rowp = base + (size_t)row * ld + colt + wc * 32 + 8 * fq;
;                 const int t = row & 2047, grow = t >> 6, gcol = t & 63;
; #pragma unroll
;                 for (int bj = 0; bj < 2; ++bj) {
;                     f32x4 v0 = acc[ai][bj][m][0], v1 = acc[ai][bj][m][1];
;                     if (kind == 1 || kind == 2) {
;                         f32x4 cs, sn;
;                         if (MODE == 0) { const int pos = (wc & 1) ? gcol : grow; const float* tp = tab + pos * 16 + 4 * fq; cs = *(const f32x4*)tp; sn = *(const f32x4*)(tp + 1024); }
;                         else { const int pos = bj ? gcol : grow; const float* tp = tab + 2048 + pos * 64 + 16 * wc + 4 * fq; cs = *(const f32x4*)tp; sn = *(const f32x4*)(tp + 4096); }
;                         const f32x4 o0 = v0 * cs - v1 * sn, o1 = v0 * sn + v1 * cs; v0 = o0; v1 = o1;
;                     }
;                     if (kind == 2 || kind == 4) { v0 = v0 * ksc; v1 = v1 * ksc; }
;                     if (kind == 3) {
; #pragma unroll
;                         for (int e = 0; e < 4; ++e) { v0[e] = silu_f(v0[e]); v1[e] = silu_f(v1[e]); }
;                     }
;                     u32x4 w; w.x = cvt_pk_bf16(v0[0], v0[1]); w.y = cvt_pk_bf16(v0[2], v0[3]); w.z = cvt_pk_bf16(v1[0], v1[1]); w.w = cvt_pk_bf16(v1[2], v1[3]);
;                     *(u32x4*)(rowp + bj * 128) = w;
.LBB0_712:
	v_or_b32_e32 v112, 16, v165
	v_mad_i64_i32 v[112:113], s[2:3], s66, v112, 0
	v_lshl_add_u64 v[112:113], v[112:113], 1, v[158:159]
	s_and_b64 vcc, exec, s[38:39]
	v_cvt_pk_bf16_f32 v108, v108, v109
	v_cvt_pk_bf16_f32 v109, v110, v111
	v_cvt_pk_bf16_f32 v110, v104, v105
	v_cvt_pk_bf16_f32 v111, v106, v107
	v_add_u32_e32 v230, 0x100, v229
	v_lshl_add_u64 v[232:233], s[100:101], 0, v[230:231]
	v_cndmask_b32_e64 v112, v112, v232, s[98:99]
	v_cndmask_b32_e64 v113, v113, v233, s[98:99]

;     __device__ __forceinline__ void operator()(const f32x4 (&acc)[2][2][4][2], const pg8::Unit& u, int wr, int wc, int fr, int fq) const {
;     ...
;                     *(u32x4*)(rowp + bj * 128) = w;
	global_store_dwordx4 v[112:113], v[108:111], off
	s_cbranch_vccz .LBB0_789
	s_cmp_gt_i32 s57, 3
	s_mov_b64 s[2:3], -1
	s_cbranch_scc0 .LBB0_790

; __device__ __forceinline__ unsigned cvt_pk_bf16(float lo, float hi) { unsigned r; asm volatile("v_cvt_pk_bf16_f32 %0, %1, %2" : "=v"(r) : "v"(lo), "v"(hi)); return r; }
;     __device__ __forceinline__ void operator()(const f32x4 (&acc)[2][2][4][2], const pg8::Unit& u, int wr, int wc, int fr, int fq) const {
;     ...
;                     u32x4 w; w.x = cvt_pk_bf16(v0[0], v0[1]); w.y = cvt_pk_bf16(v0[2], v0[3]); w.z = cvt_pk_bf16(v1[0], v1[1]); w.w = cvt_pk_bf16(v1[2], v1[3]);
;                     *(u32x4*)(rowp + bj * 128) = w;
.LBB0_717:
	s_and_b64 vcc, exec, s[38:39]
	v_cvt_pk_bf16_f32 v100, v100, v101
	v_cvt_pk_bf16_f32 v101, v102, v103
	v_cvt_pk_bf16_f32 v102, v96, v97
	v_cvt_pk_bf16_f32 v103, v98, v99
	v_lshl_add_u64 v[112:113], v[112:113], 0, v[234:235]

;     __device__ __forceinline__ void operator()(const f32x4 (&acc)[2][2][4][2], const pg8::Unit& u, int wr, int wc, int fr, int fq) const {
;     ...
;                     *(u32x4*)(rowp + bj * 128) = w;
	global_store_dwordx4 v[112:113], v[100:103], off offset:256
	s_cbranch_vccz .LBB0_792
	s_cmp_gt_i32 s57, 3
	s_mov_b64 s[2:3], -1
	s_cbranch_scc0 .LBB0_793

; __device__ __forceinline__ unsigned cvt_pk_bf16(float lo, float hi) { unsigned r; asm volatile("v_cvt_pk_bf16_f32 %0, %1, %2" : "=v"(r) : "v"(lo), "v"(hi)); return r; }
; __device__ __forceinline__ float silu_f(float v) { return v * __builtin_amdgcn_rcpf(1.f + __builtin_amdgcn_exp2f(-v * LOG2E)); }
;     __device__ __forceinline__ void operator()(const f32x4 (&acc)[2][2][4][2], const pg8::Unit& u, int wr, int wc, int fr, int fq) const {
;     ...
;                 const int row = row0 + ai * 128 + m * 16;
;                 bf16_t* rowp = base + (size_t)row * ld + colt + wc * 32 + 8 * fq;
;                 const int t = row & 2047, grow = t >> 6, gcol = t & 63;
; #pragma unroll
;                 for (int bj = 0; bj < 2; ++bj) {
;                     f32x4 v0 = acc[ai][bj][m][0], v1 = acc[ai][bj][m][1];
;                     if (kind == 1 || kind == 2) {
;                         f32x4 cs, sn;
;                         if (MODE == 0) { const int pos = (wc & 1) ? gcol : grow; const float* tp = tab + pos * 16 + 4 * fq; cs = *(const f32x4*)tp; sn = *(const f32x4*)(tp + 1024); }
;                         else { const int pos = bj ? gcol : grow; const float* tp = tab + 2048 + pos * 64 + 16 * wc + 4 * fq; cs = *(const f32x4*)tp; sn = *(const f32x4*)(tp + 4096); }
;                         const f32x4 o0 = v0 * cs - v1 * sn, o1 = v0 * sn + v1 * cs; v0 = o0; v1 = o1;
;                     }
;                     if (kind == 2 || kind == 4) { v0 = v0 * ksc; v1 = v1 * ksc; }
;                     if (kind == 3) {
; #pragma unroll
;                         for (int e = 0; e < 4; ++e) { v0[e] = silu_f(v0[e]); v1[e] = silu_f(v1[e]); }
;                     }
;                     u32x4 w; w.x = cvt_pk_bf16(v0[0], v0[1]); w.y = cvt_pk_bf16(v0[2], v0[3]); w.z = cvt_pk_bf16(v1[0], v1[1]); w.w = cvt_pk_bf16(v1[2], v1[3]);
;                     *(u32x4*)(rowp + bj * 128) = w;
.LBB0_722:
	v_or_b32_e32 v96, 32, v165
	v_mad_i64_i32 v[96:97], s[2:3], s66, v96, 0
	v_lshl_add_u64 v[96:97], v[96:97], 1, v[158:159]
	s_and_b64 vcc, exec, s[38:39]
	v_cvt_pk_bf16_f32 v92, v92, v93
	v_cvt_pk_bf16_f32 v93, v94, v95
	v_cvt_pk_bf16_f32 v94, v88, v89
	v_cvt_pk_bf16_f32 v95, v90, v91
	v_add_u32_e32 v230, 0x10000, v229
	v_lshl_add_u64 v[232:233], s[100:101], 0, v[230:231]
	v_cndmask_b32_e64 v96, v96, v232, s[98:99]
	v_cndmask_b32_e64 v97, v97, v233, s[98:99]

; __device__ __forceinline__ unsigned cvt_pk_bf16(float lo, float hi) { unsigned r; asm volatile("v_cvt_pk_bf16_f32 %0, %1, %2" : "=v"(r) : "v"(lo), "v"(hi)); return r; }
; __device__ __forceinline__ float silu_f(float v) { return v * __builtin_amdgcn_rcpf(1.f + __builtin_amdgcn_exp2f(-v * LOG2E)); }
;     __device__ __forceinline__ void operator()(const f32x4 (&acc)[2][2][4][2], const pg8::Unit& u, int wr, int wc, int fr, int fq) const {
;     ...
;                     if (kind == 1 || kind == 2) {
;                         f32x4 cs, sn;
;                         if (MODE == 0) { const int pos = (wc & 1) ? gcol : grow; const float* tp = tab + pos * 16 + 4 * fq; cs = *(const f32x4*)tp; sn = *(const f32x4*)(tp + 1024); }
;                         else { const int pos = bj ? gcol : grow; const float* tp = tab + 2048 + pos * 64 + 16 * wc + 4 * fq; cs = *(const f32x4*)tp; sn = *(const f32x4*)(tp + 4096); }
;                         const f32x4 o0 = v0 * cs - v1 * sn, o1 = v0 * sn + v1 * cs; v0 = o0; v1 = o1;
;                     }
;                     if (kind == 2 || kind == 4) { v0 = v0 * ksc; v1 = v1 * ksc; }
;                     if (kind == 3) {
; #pragma unroll
;                         for (int e = 0; e < 4; ++e) { v0[e] = silu_f(v0[e]); v1[e] = silu_f(v1[e]); }
;                     }
;                     u32x4 w; w.x = cvt_pk_bf16(v0[0], v0[1]); w.y = cvt_pk_bf16(v0[2], v0[3]); w.z = cvt_pk_bf16(v1[0], v1[1]); w.w = cvt_pk_bf16(v1[2], v1[3]);
;                     *(u32x4*)(rowp + bj * 128) = w;
	global_store_dwordx4 v[96:97], v[92:95], off
	s_cbranch_vccz .LBB0_795
	s_cmp_gt_i32 s57, 3
	s_mov_b64 s[2:3], -1
	s_cbranch_scc0 .LBB0_796

; __device__ __forceinline__ unsigned cvt_pk_bf16(float lo, float hi) { unsigned r; asm volatile("v_cvt_pk_bf16_f32 %0, %1, %2" : "=v"(r) : "v"(lo), "v"(hi)); return r; }
; __device__ __forceinline__ float silu_f(float v) { return v * __builtin_amdgcn_rcpf(1.f + __builtin_amdgcn_exp2f(-v * LOG2E)); }
;     __device__ __forceinline__ void operator()(const f32x4 (&acc)[2][2][4][2], const pg8::Unit& u, int wr, int wc, int fr, int fq) const {
;     ...
;                     if (kind == 1 || kind == 2) {
;                         f32x4 cs, sn;
;                         if (MODE == 0) { const int pos = (wc & 1) ? gcol : grow; const float* tp = tab + pos * 16 + 4 * fq; cs = *(const f32x4*)tp; sn = *(const f32x4*)(tp + 1024); }
;                         else { const int pos = bj ? gcol : grow; const float* tp = tab + 2048 + pos * 64 + 16 * wc + 4 * fq; cs = *(const f32x4*)tp; sn = *(const f32x4*)(tp + 4096); }
;                         const f32x4 o0 = v0 * cs - v1 * sn, o1 = v0 * sn + v1 * cs; v0 = o0; v1 = o1;
;                     }
;                     if (kind == 2 || kind == 4) { v0 = v0 * ksc; v1 = v1 * ksc; }
;                     if (kind == 3) {
; #pragma unroll
;                         for (int e = 0; e < 4; ++e) { v0[e] = silu_f(v0[e]); v1[e] = silu_f(v1[e]); }
;                     }
;                     u32x4 w; w.x = cvt_pk_bf16(v0[0], v0[1]); w.y = cvt_pk_bf16(v0[2], v0[3]); w.z = cvt_pk_bf16(v1[0], v1[1]); w.w = cvt_pk_bf16(v1[2], v1[3]);
;                     *(u32x4*)(rowp + bj * 128) = w;
.LBB0_727:
	s_and_b64 vcc, exec, s[38:39]
	v_cvt_pk_bf16_f32 v84, v84, v85
	v_cvt_pk_bf16_f32 v85, v86, v87
	v_cvt_pk_bf16_f32 v86, v80, v81
	v_cvt_pk_bf16_f32 v87, v82, v83
	v_lshl_add_u64 v[96:97], v[96:97], 0, v[234:235]

; __device__ __forceinline__ unsigned cvt_pk_bf16(float lo, float hi) { unsigned r; asm volatile("v_cvt_pk_bf16_f32 %0, %1, %2" : "=v"(r) : "v"(lo), "v"(hi)); return r; }
; __device__ __forceinline__ float silu_f(float v) { return v * __builtin_amdgcn_rcpf(1.f + __builtin_amdgcn_exp2f(-v * LOG2E)); }
;     __device__ __forceinline__ void operator()(const f32x4 (&acc)[2][2][4][2], const pg8::Unit& u, int wr, int wc, int fr, int fq) const {
;     ...
;                     if (kind == 1 || kind == 2) {
;                         f32x4 cs, sn;
;                         if (MODE == 0) { const int pos = (wc & 1) ? gcol : grow; const float* tp = tab + pos * 16 + 4 * fq; cs = *(const f32x4*)tp; sn = *(const f32x4*)(tp + 1024); }
;                         else { const int pos = bj ? gcol : grow; const float* tp = tab + 2048 + pos * 64 + 16 * wc + 4 * fq; cs = *(const f32x4*)tp; sn = *(const f32x4*)(tp + 4096); }
;                         const f32x4 o0 = v0 * cs - v1 * sn, o1 = v0 * sn + v1 * cs; v0 = o0; v1 = o1;
;                     }
;                     if (kind == 2 || kind == 4) { v0 = v0 * ksc; v1 = v1 * ksc; }
;                     if (kind == 3) {
; #pragma unroll
;                         for (int e = 0; e < 4; ++e) { v0[e] = silu_f(v0[e]); v1[e] = silu_f(v1[e]); }
;                     }
;                     u32x4 w; w.x = cvt_pk_bf16(v0[0], v0[1]); w.y = cvt_pk_bf16(v0[2], v0[3]); w.z = cvt_pk_bf16(v1[0], v1[1]); w.w = cvt_pk_bf16(v1[2], v1[3]);
;                     *(u32x4*)(rowp + bj * 128) = w;
	global_store_dwordx4 v[96:97], v[84:87], off offset:256
	s_cbranch_vccz .LBB0_798
	s_cmp_gt_i32 s57, 3
	s_mov_b64 s[2:3], -1
	s_cbranch_scc0 .LBB0_799

; __device__ __forceinline__ unsigned cvt_pk_bf16(float lo, float hi) { unsigned r; asm volatile("v_cvt_pk_bf16_f32 %0, %1, %2" : "=v"(r) : "v"(lo), "v"(hi)); return r; }
; __device__ __forceinline__ float silu_f(float v) { return v * __builtin_amdgcn_rcpf(1.f + __builtin_amdgcn_exp2f(-v * LOG2E)); }
;     __device__ __forceinline__ void operator()(const f32x4 (&acc)[2][2][4][2], const pg8::Unit& u, int wr, int wc, int fr, int fq) const {
;     ...
;                 const int row = row0 + ai * 128 + m * 16;
;                 bf16_t* rowp = base + (size_t)row * ld + colt + wc * 32 + 8 * fq;
;                 const int t = row & 2047, grow = t >> 6, gcol = t & 63;
; #pragma unroll
;                 for (int bj = 0; bj < 2; ++bj) {
;                     f32x4 v0 = acc[ai][bj][m][0], v1 = acc[ai][bj][m][1];
;                     if (kind == 1 || kind == 2) {
;                         f32x4 cs, sn;
;                         if (MODE == 0) { const int pos = (wc & 1) ? gcol : grow; const float* tp = tab + pos * 16 + 4 * fq; cs = *(const f32x4*)tp; sn = *(const f32x4*)(tp + 1024); }
;                         else { const int pos = bj ? gcol : grow; const float* tp = tab + 2048 + pos * 64 + 16 * wc + 4 * fq; cs = *(const f32x4*)tp; sn = *(const f32x4*)(tp + 4096); }
;                         const f32x4 o0 = v0 * cs - v1 * sn, o1 = v0 * sn + v1 * cs; v0 = o0; v1 = o1;
;                     }
;                     if (kind == 2 || kind == 4) { v0 = v0 * ksc; v1 = v1 * ksc; }
;                     if (kind == 3) {
; #pragma unroll
;                         for (int e = 0; e < 4; ++e) { v0[e] = silu_f(v0[e]); v1[e] = silu_f(v1[e]); }
;                     }
;                     u32x4 w; w.x = cvt_pk_bf16(v0[0], v0[1]); w.y = cvt_pk_bf16(v0[2], v0[3]); w.z = cvt_pk_bf16(v1[0], v1[1]); w.w = cvt_pk_bf16(v1[2], v1[3]);
;                     *(u32x4*)(rowp + bj * 128) = w;
.LBB0_732:
	v_or_b32_e32 v80, 48, v165
	v_mad_i64_i32 v[80:81], s[2:3], s66, v80, 0
	v_lshl_add_u64 v[80:81], v[80:81], 1, v[158:159]
	s_and_b64 vcc, exec, s[38:39]
	v_cvt_pk_bf16_f32 v76, v76, v77
	v_cvt_pk_bf16_f32 v77, v78, v79
	v_cvt_pk_bf16_f32 v78, v72, v73
	v_cvt_pk_bf16_f32 v79, v74, v75
	v_add_u32_e32 v230, 0x10100, v229
	v_lshl_add_u64 v[232:233], s[100:101], 0, v[230:231]
	v_cndmask_b32_e64 v80, v80, v232, s[98:99]
	v_cndmask_b32_e64 v81, v81, v233, s[98:99]

; __device__ __forceinline__ unsigned cvt_pk_bf16(float lo, float hi) { unsigned r; asm volatile("v_cvt_pk_bf16_f32 %0, %1, %2" : "=v"(r) : "v"(lo), "v"(hi)); return r; }
; __device__ __forceinline__ float silu_f(float v) { return v * __builtin_amdgcn_rcpf(1.f + __builtin_amdgcn_exp2f(-v * LOG2E)); }
;     __device__ __forceinline__ void operator()(const f32x4 (&acc)[2][2][4][2], const pg8::Unit& u, int wr, int wc, int fr, int fq) const {
;     ...
;                     if (kind == 1 || kind == 2) {
;                         f32x4 cs, sn;
;                         if (MODE == 0) { const int pos = (wc & 1) ? gcol : grow; const float* tp = tab + pos * 16 + 4 * fq; cs = *(const f32x4*)tp; sn = *(const f32x4*)(tp + 1024); }
;                         else { const int pos = bj ? gcol : grow; const float* tp = tab + 2048 + pos * 64 + 16 * wc + 4 * fq; cs = *(const f32x4*)tp; sn = *(const f32x4*)(tp + 4096); }
;                         const f32x4 o0 = v0 * cs - v1 * sn, o1 = v0 * sn + v1 * cs; v0 = o0; v1 = o1;
;                     }
;                     if (kind == 2 || kind == 4) { v0 = v0 * ksc; v1 = v1 * ksc; }
;                     if (kind == 3) {
; #pragma unroll
;                         for (int e = 0; e < 4; ++e) { v0[e] = silu_f(v0[e]); v1[e] = silu_f(v1[e]); }
;                     }
;                     u32x4 w; w.x = cvt_pk_bf16(v0[0], v0[1]); w.y = cvt_pk_bf16(v0[2], v0[3]); w.z = cvt_pk_bf16(v1[0], v1[1]); w.w = cvt_pk_bf16(v1[2], v1[3]);
;                     *(u32x4*)(rowp + bj * 128) = w;
	global_store_dwordx4 v[80:81], v[76:79], off
	s_cbranch_vccz .LBB0_801
	s_cmp_gt_i32 s57, 3
	s_mov_b64 s[2:3], -1
	s_cbranch_scc0 .LBB0_802

; __device__ __forceinline__ unsigned cvt_pk_bf16(float lo, float hi) { unsigned r; asm volatile("v_cvt_pk_bf16_f32 %0, %1, %2" : "=v"(r) : "v"(lo), "v"(hi)); return r; }
; __device__ __forceinline__ float silu_f(float v) { return v * __builtin_amdgcn_rcpf(1.f + __builtin_amdgcn_exp2f(-v * LOG2E)); }
;     __device__ __forceinline__ void operator()(const f32x4 (&acc)[2][2][4][2], const pg8::Unit& u, int wr, int wc, int fr, int fq) const {
;     ...
;                     if (kind == 1 || kind == 2) {
;                         f32x4 cs, sn;
;                         if (MODE == 0) { const int pos = (wc & 1) ? gcol : grow; const float* tp = tab + pos * 16 + 4 * fq; cs = *(const f32x4*)tp; sn = *(const f32x4*)(tp + 1024); }
;                         else { const int pos = bj ? gcol : grow; const float* tp = tab + 2048 + pos * 64 + 16 * wc + 4 * fq; cs = *(const f32x4*)tp; sn = *(const f32x4*)(tp + 4096); }
;                         const f32x4 o0 = v0 * cs - v1 * sn, o1 = v0 * sn + v1 * cs; v0 = o0; v1 = o1;
;                     }
;                     if (kind == 2 || kind == 4) { v0 = v0 * ksc; v1 = v1 * ksc; }
;                     if (kind == 3) {
; #pragma unroll
;                         for (int e = 0; e < 4; ++e) { v0[e] = silu_f(v0[e]); v1[e] = silu_f(v1[e]); }
;                     }
;                     u32x4 w; w.x = cvt_pk_bf16(v0[0], v0[1]); w.y = cvt_pk_bf16(v0[2], v0[3]); w.z = cvt_pk_bf16(v1[0], v1[1]); w.w = cvt_pk_bf16(v1[2], v1[3]);
;                     *(u32x4*)(rowp + bj * 128) = w;
.LBB0_737:
	v_cvt_pk_bf16_f32 v68, v68, v69
	v_cvt_pk_bf16_f32 v69, v70, v71
	v_cvt_pk_bf16_f32 v70, v64, v65
	s_nop 0
	v_cvt_pk_bf16_f32 v71, v66, v67
	v_add_u32_e32 v66, 0x80, v165
	v_bfe_u32 v64, v66, 6, 5
	s_and_b64 vcc, exec, s[38:39]
	v_lshlrev_b32_e32 v64, 8, v64
	v_lshl_add_u64 v[80:81], v[80:81], 0, v[234:235]

; __device__ __forceinline__ unsigned cvt_pk_bf16(float lo, float hi) { unsigned r; asm volatile("v_cvt_pk_bf16_f32 %0, %1, %2" : "=v"(r) : "v"(lo), "v"(hi)); return r; }
; __device__ __forceinline__ float silu_f(float v) { return v * __builtin_amdgcn_rcpf(1.f + __builtin_amdgcn_exp2f(-v * LOG2E)); }
;     __device__ __forceinline__ void operator()(const f32x4 (&acc)[2][2][4][2], const pg8::Unit& u, int wr, int wc, int fr, int fq) const {
;     ...
;                     if (kind == 1 || kind == 2) {
;                         f32x4 cs, sn;
;                         if (MODE == 0) { const int pos = (wc & 1) ? gcol : grow; const float* tp = tab + pos * 16 + 4 * fq; cs = *(const f32x4*)tp; sn = *(const f32x4*)(tp + 1024); }
;                         else { const int pos = bj ? gcol : grow; const float* tp = tab + 2048 + pos * 64 + 16 * wc + 4 * fq; cs = *(const f32x4*)tp; sn = *(const f32x4*)(tp + 4096); }
;                         const f32x4 o0 = v0 * cs - v1 * sn, o1 = v0 * sn + v1 * cs; v0 = o0; v1 = o1;
;                     }
;                     if (kind == 2 || kind == 4) { v0 = v0 * ksc; v1 = v1 * ksc; }
;                     if (kind == 3) {
; #pragma unroll
;                         for (int e = 0; e < 4; ++e) { v0[e] = silu_f(v0[e]); v1[e] = silu_f(v1[e]); }
;                     }
;                     u32x4 w; w.x = cvt_pk_bf16(v0[0], v0[1]); w.y = cvt_pk_bf16(v0[2], v0[3]); w.z = cvt_pk_bf16(v1[0], v1[1]); w.w = cvt_pk_bf16(v1[2], v1[3]);
;                     *(u32x4*)(rowp + bj * 128) = w;
	global_store_dwordx4 v[80:81], v[68:71], off offset:256
	s_cbranch_vccz .LBB0_804
	s_cmp_gt_i32 s57, 3
	s_mov_b64 s[2:3], -1
	s_cbranch_scc0 .LBB0_805

; __device__ __forceinline__ unsigned cvt_pk_bf16(float lo, float hi) { unsigned r; asm volatile("v_cvt_pk_bf16_f32 %0, %1, %2" : "=v"(r) : "v"(lo), "v"(hi)); return r; }
; __device__ __forceinline__ float silu_f(float v) { return v * __builtin_amdgcn_rcpf(1.f + __builtin_amdgcn_exp2f(-v * LOG2E)); }
;     __device__ __forceinline__ void operator()(const f32x4 (&acc)[2][2][4][2], const pg8::Unit& u, int wr, int wc, int fr, int fq) const {
;     ...
;                 const int row = row0 + ai * 128 + m * 16;
;                 bf16_t* rowp = base + (size_t)row * ld + colt + wc * 32 + 8 * fq;
;                 const int t = row & 2047, grow = t >> 6, gcol = t & 63;
; #pragma unroll
;                 for (int bj = 0; bj < 2; ++bj) {
;                     f32x4 v0 = acc[ai][bj][m][0], v1 = acc[ai][bj][m][1];
;                     if (kind == 1 || kind == 2) {
;                         f32x4 cs, sn;
;                         if (MODE == 0) { const int pos = (wc & 1) ? gcol : grow; const float* tp = tab + pos * 16 + 4 * fq; cs = *(const f32x4*)tp; sn = *(const f32x4*)(tp + 1024); }
;                         else { const int pos = bj ? gcol : grow; const float* tp = tab + 2048 + pos * 64 + 16 * wc + 4 * fq; cs = *(const f32x4*)tp; sn = *(const f32x4*)(tp + 4096); }
;                         const f32x4 o0 = v0 * cs - v1 * sn, o1 = v0 * sn + v1 * cs; v0 = o0; v1 = o1;
;                     }
;                     if (kind == 2 || kind == 4) { v0 = v0 * ksc; v1 = v1 * ksc; }
;                     if (kind == 3) {
; #pragma unroll
;                         for (int e = 0; e < 4; ++e) { v0[e] = silu_f(v0[e]); v1[e] = silu_f(v1[e]); }
;                     }
;                     u32x4 w; w.x = cvt_pk_bf16(v0[0], v0[1]); w.y = cvt_pk_bf16(v0[2], v0[3]); w.z = cvt_pk_bf16(v1[0], v1[1]); w.w = cvt_pk_bf16(v1[2], v1[3]);
;                     *(u32x4*)(rowp + bj * 128) = w;
.LBB0_742:
	v_mad_i64_i32 v[66:67], s[2:3], s66, v66, 0
	v_lshl_add_u64 v[66:67], v[66:67], 1, v[158:159]
	s_and_b64 vcc, exec, s[38:39]
	v_cvt_pk_bf16_f32 v60, v60, v61
	v_cvt_pk_bf16_f32 v61, v62, v63
	v_cvt_pk_bf16_f32 v62, v56, v57
	v_cvt_pk_bf16_f32 v63, v58, v59
	v_add_u32_e32 v230, 0x40000, v229
	v_lshl_add_u64 v[232:233], s[100:101], 0, v[230:231]
	v_cndmask_b32_e64 v66, v66, v232, s[98:99]
	v_cndmask_b32_e64 v67, v67, v233, s[98:99]

; __device__ __forceinline__ unsigned cvt_pk_bf16(float lo, float hi) { unsigned r; asm volatile("v_cvt_pk_bf16_f32 %0, %1, %2" : "=v"(r) : "v"(lo), "v"(hi)); return r; }
; __device__ __forceinline__ float silu_f(float v) { return v * __builtin_amdgcn_rcpf(1.f + __builtin_amdgcn_exp2f(-v * LOG2E)); }
;     __device__ __forceinline__ void operator()(const f32x4 (&acc)[2][2][4][2], const pg8::Unit& u, int wr, int wc, int fr, int fq) const {
;     ...
;                     if (kind == 1 || kind == 2) {
;                         f32x4 cs, sn;
;                         if (MODE == 0) { const int pos = (wc & 1) ? gcol : grow; const float* tp = tab + pos * 16 + 4 * fq; cs = *(const f32x4*)tp; sn = *(const f32x4*)(tp + 1024); }
;                         else { const int pos = bj ? gcol : grow; const float* tp = tab + 2048 + pos * 64 + 16 * wc + 4 * fq; cs = *(const f32x4*)tp; sn = *(const f32x4*)(tp + 4096); }
;                         const f32x4 o0 = v0 * cs - v1 * sn, o1 = v0 * sn + v1 * cs; v0 = o0; v1 = o1;
;                     }
;                     if (kind == 2 || kind == 4) { v0 = v0 * ksc; v1 = v1 * ksc; }
;                     if (kind == 3) {
; #pragma unroll
;                         for (int e = 0; e < 4; ++e) { v0[e] = silu_f(v0[e]); v1[e] = silu_f(v1[e]); }
;                     }
;                     u32x4 w; w.x = cvt_pk_bf16(v0[0], v0[1]); w.y = cvt_pk_bf16(v0[2], v0[3]); w.z = cvt_pk_bf16(v1[0], v1[1]); w.w = cvt_pk_bf16(v1[2], v1[3]);
;                     *(u32x4*)(rowp + bj * 128) = w;
	global_store_dwordx4 v[66:67], v[60:63], off
	s_cbranch_vccz .LBB0_807
	s_cmp_gt_i32 s57, 3
	s_mov_b64 s[2:3], -1
	s_cbranch_scc0 .LBB0_808

; __device__ __forceinline__ unsigned cvt_pk_bf16(float lo, float hi) { unsigned r; asm volatile("v_cvt_pk_bf16_f32 %0, %1, %2" : "=v"(r) : "v"(lo), "v"(hi)); return r; }
; __device__ __forceinline__ float silu_f(float v) { return v * __builtin_amdgcn_rcpf(1.f + __builtin_amdgcn_exp2f(-v * LOG2E)); }
;     __device__ __forceinline__ void operator()(const f32x4 (&acc)[2][2][4][2], const pg8::Unit& u, int wr, int wc, int fr, int fq) const {
;     ...
;                     if (kind == 1 || kind == 2) {
;                         f32x4 cs, sn;
;                         if (MODE == 0) { const int pos = (wc & 1) ? gcol : grow; const float* tp = tab + pos * 16 + 4 * fq; cs = *(const f32x4*)tp; sn = *(const f32x4*)(tp + 1024); }
;                         else { const int pos = bj ? gcol : grow; const float* tp = tab + 2048 + pos * 64 + 16 * wc + 4 * fq; cs = *(const f32x4*)tp; sn = *(const f32x4*)(tp + 4096); }
;                         const f32x4 o0 = v0 * cs - v1 * sn, o1 = v0 * sn + v1 * cs; v0 = o0; v1 = o1;
;                     }
;                     if (kind == 2 || kind == 4) { v0 = v0 * ksc; v1 = v1 * ksc; }
;                     if (kind == 3) {
; #pragma unroll
;                         for (int e = 0; e < 4; ++e) { v0[e] = silu_f(v0[e]); v1[e] = silu_f(v1[e]); }
;                     }
;                     u32x4 w; w.x = cvt_pk_bf16(v0[0], v0[1]); w.y = cvt_pk_bf16(v0[2], v0[3]); w.z = cvt_pk_bf16(v1[0], v1[1]); w.w = cvt_pk_bf16(v1[2], v1[3]);
;                     *(u32x4*)(rowp + bj * 128) = w;
.LBB0_747:
	s_and_b64 vcc, exec, s[38:39]
	v_cvt_pk_bf16_f32 v52, v52, v53
	v_cvt_pk_bf16_f32 v53, v54, v55
	v_cvt_pk_bf16_f32 v54, v48, v49
	v_cvt_pk_bf16_f32 v55, v50, v51
	v_lshl_add_u64 v[66:67], v[66:67], 0, v[234:235]

; __device__ __forceinline__ unsigned cvt_pk_bf16(float lo, float hi) { unsigned r; asm volatile("v_cvt_pk_bf16_f32 %0, %1, %2" : "=v"(r) : "v"(lo), "v"(hi)); return r; }
; __device__ __forceinline__ float silu_f(float v) { return v * __builtin_amdgcn_rcpf(1.f + __builtin_amdgcn_exp2f(-v * LOG2E)); }
;     __device__ __forceinline__ void operator()(const f32x4 (&acc)[2][2][4][2], const pg8::Unit& u, int wr, int wc, int fr, int fq) const {
;     ...
;                     if (kind == 1 || kind == 2) {
;                         f32x4 cs, sn;
;                         if (MODE == 0) { const int pos = (wc & 1) ? gcol : grow; const float* tp = tab + pos * 16 + 4 * fq; cs = *(const f32x4*)tp; sn = *(const f32x4*)(tp + 1024); }
;                         else { const int pos = bj ? gcol : grow; const float* tp = tab + 2048 + pos * 64 + 16 * wc + 4 * fq; cs = *(const f32x4*)tp; sn = *(const f32x4*)(tp + 4096); }
;                         const f32x4 o0 = v0 * cs - v1 * sn, o1 = v0 * sn + v1 * cs; v0 = o0; v1 = o1;
;                     }
;                     if (kind == 2 || kind == 4) { v0 = v0 * ksc; v1 = v1 * ksc; }
;                     if (kind == 3) {
; #pragma unroll
;                         for (int e = 0; e < 4; ++e) { v0[e] = silu_f(v0[e]); v1[e] = silu_f(v1[e]); }
;                     }
;                     u32x4 w; w.x = cvt_pk_bf16(v0[0], v0[1]); w.y = cvt_pk_bf16(v0[2], v0[3]); w.z = cvt_pk_bf16(v1[0], v1[1]); w.w = cvt_pk_bf16(v1[2], v1[3]);
;                     *(u32x4*)(rowp + bj * 128) = w;
	global_store_dwordx4 v[66:67], v[52:55], off offset:256
	s_cbranch_vccz .LBB0_810
	s_cmp_gt_i32 s57, 3
	s_mov_b64 s[2:3], -1
	s_cbranch_scc0 .LBB0_811

; __device__ __forceinline__ unsigned cvt_pk_bf16(float lo, float hi) { unsigned r; asm volatile("v_cvt_pk_bf16_f32 %0, %1, %2" : "=v"(r) : "v"(lo), "v"(hi)); return r; }
; __device__ __forceinline__ float silu_f(float v) { return v * __builtin_amdgcn_rcpf(1.f + __builtin_amdgcn_exp2f(-v * LOG2E)); }
;     __device__ __forceinline__ void operator()(const f32x4 (&acc)[2][2][4][2], const pg8::Unit& u, int wr, int wc, int fr, int fq) const {
;     ...
;                 const int row = row0 + ai * 128 + m * 16;
;                 bf16_t* rowp = base + (size_t)row * ld + colt + wc * 32 + 8 * fq;
;                 const int t = row & 2047, grow = t >> 6, gcol = t & 63;
; #pragma unroll
;                 for (int bj = 0; bj < 2; ++bj) {
;                     f32x4 v0 = acc[ai][bj][m][0], v1 = acc[ai][bj][m][1];
;                     if (kind == 1 || kind == 2) {
;                         f32x4 cs, sn;
;                         if (MODE == 0) { const int pos = (wc & 1) ? gcol : grow; const float* tp = tab + pos * 16 + 4 * fq; cs = *(const f32x4*)tp; sn = *(const f32x4*)(tp + 1024); }
;                         else { const int pos = bj ? gcol : grow; const float* tp = tab + 2048 + pos * 64 + 16 * wc + 4 * fq; cs = *(const f32x4*)tp; sn = *(const f32x4*)(tp + 4096); }
;                         const f32x4 o0 = v0 * cs - v1 * sn, o1 = v0 * sn + v1 * cs; v0 = o0; v1 = o1;
;                     }
;                     if (kind == 2 || kind == 4) { v0 = v0 * ksc; v1 = v1 * ksc; }
;                     if (kind == 3) {
; #pragma unroll
;                         for (int e = 0; e < 4; ++e) { v0[e] = silu_f(v0[e]); v1[e] = silu_f(v1[e]); }
;                     }
;                     u32x4 w; w.x = cvt_pk_bf16(v0[0], v0[1]); w.y = cvt_pk_bf16(v0[2], v0[3]); w.z = cvt_pk_bf16(v1[0], v1[1]); w.w = cvt_pk_bf16(v1[2], v1[3]);
;                     *(u32x4*)(rowp + bj * 128) = w;
.LBB0_752:
	v_add_u32_e32 v48, 0x90, v165
	v_mad_i64_i32 v[48:49], s[2:3], s66, v48, 0
	v_lshl_add_u64 v[48:49], v[48:49], 1, v[158:159]
	s_and_b64 vcc, exec, s[38:39]
	v_cvt_pk_bf16_f32 v44, v44, v45
	v_cvt_pk_bf16_f32 v45, v46, v47
	v_cvt_pk_bf16_f32 v46, v40, v41
	v_cvt_pk_bf16_f32 v47, v42, v43
	v_add_u32_e32 v230, 0x40100, v229
	v_lshl_add_u64 v[232:233], s[100:101], 0, v[230:231]
	v_cndmask_b32_e64 v48, v48, v232, s[98:99]
	v_cndmask_b32_e64 v49, v49, v233, s[98:99]

; __device__ __forceinline__ unsigned cvt_pk_bf16(float lo, float hi) { unsigned r; asm volatile("v_cvt_pk_bf16_f32 %0, %1, %2" : "=v"(r) : "v"(lo), "v"(hi)); return r; }
; __device__ __forceinline__ float silu_f(float v) { return v * __builtin_amdgcn_rcpf(1.f + __builtin_amdgcn_exp2f(-v * LOG2E)); }
;     __device__ __forceinline__ void operator()(const f32x4 (&acc)[2][2][4][2], const pg8::Unit& u, int wr, int wc, int fr, int fq) const {
;     ...
;                     if (kind == 1 || kind == 2) {
;                         f32x4 cs, sn;
;                         if (MODE == 0) { const int pos = (wc & 1) ? gcol : grow; const float* tp = tab + pos * 16 + 4 * fq; cs = *(const f32x4*)tp; sn = *(const f32x4*)(tp + 1024); }
;                         else { const int pos = bj ? gcol : grow; const float* tp = tab + 2048 + pos * 64 + 16 * wc + 4 * fq; cs = *(const f32x4*)tp; sn = *(const f32x4*)(tp + 4096); }
;                         const f32x4 o0 = v0 * cs - v1 * sn, o1 = v0 * sn + v1 * cs; v0 = o0; v1 = o1;
;                     }
;                     if (kind == 2 || kind == 4) { v0 = v0 * ksc; v1 = v1 * ksc; }
;                     if (kind == 3) {
; #pragma unroll
;                         for (int e = 0; e < 4; ++e) { v0[e] = silu_f(v0[e]); v1[e] = silu_f(v1[e]); }
;                     }
;                     u32x4 w; w.x = cvt_pk_bf16(v0[0], v0[1]); w.y = cvt_pk_bf16(v0[2], v0[3]); w.z = cvt_pk_bf16(v1[0], v1[1]); w.w = cvt_pk_bf16(v1[2], v1[3]);
;                     *(u32x4*)(rowp + bj * 128) = w;
	global_store_dwordx4 v[48:49], v[44:47], off
	s_cbranch_vccz .LBB0_813
	s_cmp_gt_i32 s57, 3
	s_mov_b64 s[2:3], -1
	s_cbranch_scc0 .LBB0_814

; __device__ __forceinline__ unsigned cvt_pk_bf16(float lo, float hi) { unsigned r; asm volatile("v_cvt_pk_bf16_f32 %0, %1, %2" : "=v"(r) : "v"(lo), "v"(hi)); return r; }
; __device__ __forceinline__ float silu_f(float v) { return v * __builtin_amdgcn_rcpf(1.f + __builtin_amdgcn_exp2f(-v * LOG2E)); }
;     __device__ __forceinline__ void operator()(const f32x4 (&acc)[2][2][4][2], const pg8::Unit& u, int wr, int wc, int fr, int fq) const {
;     ...
;                     if (kind == 1 || kind == 2) {
;                         f32x4 cs, sn;
;                         if (MODE == 0) { const int pos = (wc & 1) ? gcol : grow; const float* tp = tab + pos * 16 + 4 * fq; cs = *(const f32x4*)tp; sn = *(const f32x4*)(tp + 1024); }
;                         else { const int pos = bj ? gcol : grow; const float* tp = tab + 2048 + pos * 64 + 16 * wc + 4 * fq; cs = *(const f32x4*)tp; sn = *(const f32x4*)(tp + 4096); }
;                         const f32x4 o0 = v0 * cs - v1 * sn, o1 = v0 * sn + v1 * cs; v0 = o0; v1 = o1;
;                     }
;                     if (kind == 2 || kind == 4) { v0 = v0 * ksc; v1 = v1 * ksc; }
;                     if (kind == 3) {
; #pragma unroll
;                         for (int e = 0; e < 4; ++e) { v0[e] = silu_f(v0[e]); v1[e] = silu_f(v1[e]); }
;                     }
;                     u32x4 w; w.x = cvt_pk_bf16(v0[0], v0[1]); w.y = cvt_pk_bf16(v0[2], v0[3]); w.z = cvt_pk_bf16(v1[0], v1[1]); w.w = cvt_pk_bf16(v1[2], v1[3]);
;                     *(u32x4*)(rowp + bj * 128) = w;
.LBB0_757:
	s_and_b64 vcc, exec, s[38:39]
	v_cvt_pk_bf16_f32 v36, v36, v37
	v_cvt_pk_bf16_f32 v37, v38, v39
	v_cvt_pk_bf16_f32 v38, v32, v33
	v_cvt_pk_bf16_f32 v39, v34, v35
	v_lshl_add_u64 v[48:49], v[48:49], 0, v[234:235]

; __device__ __forceinline__ unsigned cvt_pk_bf16(float lo, float hi) { unsigned r; asm volatile("v_cvt_pk_bf16_f32 %0, %1, %2" : "=v"(r) : "v"(lo), "v"(hi)); return r; }
; __device__ __forceinline__ float silu_f(float v) { return v * __builtin_amdgcn_rcpf(1.f + __builtin_amdgcn_exp2f(-v * LOG2E)); }
;     __device__ __forceinline__ void operator()(const f32x4 (&acc)[2][2][4][2], const pg8::Unit& u, int wr, int wc, int fr, int fq) const {
;     ...
;                     if (kind == 1 || kind == 2) {
;                         f32x4 cs, sn;
;                         if (MODE == 0) { const int pos = (wc & 1) ? gcol : grow; const float* tp = tab + pos * 16 + 4 * fq; cs = *(const f32x4*)tp; sn = *(const f32x4*)(tp + 1024); }
;                         else { const int pos = bj ? gcol : grow; const float* tp = tab + 2048 + pos * 64 + 16 * wc + 4 * fq; cs = *(const f32x4*)tp; sn = *(const f32x4*)(tp + 4096); }
;                         const f32x4 o0 = v0 * cs - v1 * sn, o1 = v0 * sn + v1 * cs; v0 = o0; v1 = o1;
;                     }
;                     if (kind == 2 || kind == 4) { v0 = v0 * ksc; v1 = v1 * ksc; }
;                     if (kind == 3) {
; #pragma unroll
;                         for (int e = 0; e < 4; ++e) { v0[e] = silu_f(v0[e]); v1[e] = silu_f(v1[e]); }
;                     }
;                     u32x4 w; w.x = cvt_pk_bf16(v0[0], v0[1]); w.y = cvt_pk_bf16(v0[2], v0[3]); w.z = cvt_pk_bf16(v1[0], v1[1]); w.w = cvt_pk_bf16(v1[2], v1[3]);
;                     *(u32x4*)(rowp + bj * 128) = w;
	global_store_dwordx4 v[48:49], v[36:39], off offset:256
	s_cbranch_vccz .LBB0_816
	s_cmp_gt_i32 s57, 3
	s_mov_b64 s[2:3], -1
	s_cbranch_scc0 .LBB0_817

; __device__ __forceinline__ unsigned cvt_pk_bf16(float lo, float hi) { unsigned r; asm volatile("v_cvt_pk_bf16_f32 %0, %1, %2" : "=v"(r) : "v"(lo), "v"(hi)); return r; }
; __device__ __forceinline__ float silu_f(float v) { return v * __builtin_amdgcn_rcpf(1.f + __builtin_amdgcn_exp2f(-v * LOG2E)); }
;     __device__ __forceinline__ void operator()(const f32x4 (&acc)[2][2][4][2], const pg8::Unit& u, int wr, int wc, int fr, int fq) const {
;     ...
;                 const int row = row0 + ai * 128 + m * 16;
;                 bf16_t* rowp = base + (size_t)row * ld + colt + wc * 32 + 8 * fq;
;                 const int t = row & 2047, grow = t >> 6, gcol = t & 63;
; #pragma unroll
;                 for (int bj = 0; bj < 2; ++bj) {
;                     f32x4 v0 = acc[ai][bj][m][0], v1 = acc[ai][bj][m][1];
;                     if (kind == 1 || kind == 2) {
;                         f32x4 cs, sn;
;                         if (MODE == 0) { const int pos = (wc & 1) ? gcol : grow; const float* tp = tab + pos * 16 + 4 * fq; cs = *(const f32x4*)tp; sn = *(const f32x4*)(tp + 1024); }
;                         else { const int pos = bj ? gcol : grow; const float* tp = tab + 2048 + pos * 64 + 16 * wc + 4 * fq; cs = *(const f32x4*)tp; sn = *(const f32x4*)(tp + 4096); }
;                         const f32x4 o0 = v0 * cs - v1 * sn, o1 = v0 * sn + v1 * cs; v0 = o0; v1 = o1;
;                     }
;                     if (kind == 2 || kind == 4) { v0 = v0 * ksc; v1 = v1 * ksc; }
;                     if (kind == 3) {
; #pragma unroll
;                         for (int e = 0; e < 4; ++e) { v0[e] = silu_f(v0[e]); v1[e] = silu_f(v1[e]); }
;                     }
;                     u32x4 w; w.x = cvt_pk_bf16(v0[0], v0[1]); w.y = cvt_pk_bf16(v0[2], v0[3]); w.z = cvt_pk_bf16(v1[0], v1[1]); w.w = cvt_pk_bf16(v1[2], v1[3]);
;                     *(u32x4*)(rowp + bj * 128) = w;
.LBB0_762:
	v_add_u32_e32 v32, 0xa0, v165
	v_mad_i64_i32 v[32:33], s[2:3], s66, v32, 0
	v_lshl_add_u64 v[32:33], v[32:33], 1, v[158:159]
	s_and_b64 vcc, exec, s[38:39]
	v_cvt_pk_bf16_f32 v28, v28, v29
	v_cvt_pk_bf16_f32 v29, v30, v31
	v_cvt_pk_bf16_f32 v30, v24, v25
	v_cvt_pk_bf16_f32 v31, v26, v27
	v_add_u32_e32 v230, 0x50000, v229
	v_lshl_add_u64 v[232:233], s[100:101], 0, v[230:231]
	v_cndmask_b32_e64 v32, v32, v232, s[98:99]
	v_cndmask_b32_e64 v33, v33, v233, s[98:99]

; __device__ __forceinline__ unsigned cvt_pk_bf16(float lo, float hi) { unsigned r; asm volatile("v_cvt_pk_bf16_f32 %0, %1, %2" : "=v"(r) : "v"(lo), "v"(hi)); return r; }
; __device__ __forceinline__ float silu_f(float v) { return v * __builtin_amdgcn_rcpf(1.f + __builtin_amdgcn_exp2f(-v * LOG2E)); }
;     __device__ __forceinline__ void operator()(const f32x4 (&acc)[2][2][4][2], const pg8::Unit& u, int wr, int wc, int fr, int fq) const {
;     ...
;                     if (kind == 1 || kind == 2) {
;                         f32x4 cs, sn;
;                         if (MODE == 0) { const int pos = (wc & 1) ? gcol : grow; const float* tp = tab + pos * 16 + 4 * fq; cs = *(const f32x4*)tp; sn = *(const f32x4*)(tp + 1024); }
;                         else { const int pos = bj ? gcol : grow; const float* tp = tab + 2048 + pos * 64 + 16 * wc + 4 * fq; cs = *(const f32x4*)tp; sn = *(const f32x4*)(tp + 4096); }
;                         const f32x4 o0 = v0 * cs - v1 * sn, o1 = v0 * sn + v1 * cs; v0 = o0; v1 = o1;
;                     }
;                     if (kind == 2 || kind == 4) { v0 = v0 * ksc; v1 = v1 * ksc; }
;                     if (kind == 3) {
; #pragma unroll
;                         for (int e = 0; e < 4; ++e) { v0[e] = silu_f(v0[e]); v1[e] = silu_f(v1[e]); }
;                     }
;                     u32x4 w; w.x = cvt_pk_bf16(v0[0], v0[1]); w.y = cvt_pk_bf16(v0[2], v0[3]); w.z = cvt_pk_bf16(v1[0], v1[1]); w.w = cvt_pk_bf16(v1[2], v1[3]);
;                     *(u32x4*)(rowp + bj * 128) = w;
	global_store_dwordx4 v[32:33], v[28:31], off
	s_cbranch_vccz .LBB0_819
	s_cmp_gt_i32 s57, 3
	s_mov_b64 s[2:3], -1
	s_cbranch_scc0 .LBB0_820

; __device__ __forceinline__ unsigned cvt_pk_bf16(float lo, float hi) { unsigned r; asm volatile("v_cvt_pk_bf16_f32 %0, %1, %2" : "=v"(r) : "v"(lo), "v"(hi)); return r; }
; __device__ __forceinline__ float silu_f(float v) { return v * __builtin_amdgcn_rcpf(1.f + __builtin_amdgcn_exp2f(-v * LOG2E)); }
;     __device__ __forceinline__ void operator()(const f32x4 (&acc)[2][2][4][2], const pg8::Unit& u, int wr, int wc, int fr, int fq) const {
;     ...
;                     if (kind == 1 || kind == 2) {
;                         f32x4 cs, sn;
;                         if (MODE == 0) { const int pos = (wc & 1) ? gcol : grow; const float* tp = tab + pos * 16 + 4 * fq; cs = *(const f32x4*)tp; sn = *(const f32x4*)(tp + 1024); }
;                         else { const int pos = bj ? gcol : grow; const float* tp = tab + 2048 + pos * 64 + 16 * wc + 4 * fq; cs = *(const f32x4*)tp; sn = *(const f32x4*)(tp + 4096); }
;                         const f32x4 o0 = v0 * cs - v1 * sn, o1 = v0 * sn + v1 * cs; v0 = o0; v1 = o1;
;                     }
;                     if (kind == 2 || kind == 4) { v0 = v0 * ksc; v1 = v1 * ksc; }
;                     if (kind == 3) {
; #pragma unroll
;                         for (int e = 0; e < 4; ++e) { v0[e] = silu_f(v0[e]); v1[e] = silu_f(v1[e]); }
;                     }
;                     u32x4 w; w.x = cvt_pk_bf16(v0[0], v0[1]); w.y = cvt_pk_bf16(v0[2], v0[3]); w.z = cvt_pk_bf16(v1[0], v1[1]); w.w = cvt_pk_bf16(v1[2], v1[3]);
;                     *(u32x4*)(rowp + bj * 128) = w;
.LBB0_767:
	s_and_b64 vcc, exec, s[38:39]
	v_cvt_pk_bf16_f32 v20, v20, v21
	v_cvt_pk_bf16_f32 v21, v22, v23
	v_cvt_pk_bf16_f32 v22, v16, v17
	v_cvt_pk_bf16_f32 v23, v18, v19
	v_lshl_add_u64 v[32:33], v[32:33], 0, v[234:235]

; __device__ __forceinline__ unsigned cvt_pk_bf16(float lo, float hi) { unsigned r; asm volatile("v_cvt_pk_bf16_f32 %0, %1, %2" : "=v"(r) : "v"(lo), "v"(hi)); return r; }
; __device__ __forceinline__ float silu_f(float v) { return v * __builtin_amdgcn_rcpf(1.f + __builtin_amdgcn_exp2f(-v * LOG2E)); }
;     __device__ __forceinline__ void operator()(const f32x4 (&acc)[2][2][4][2], const pg8::Unit& u, int wr, int wc, int fr, int fq) const {
;     ...
;                     if (kind == 1 || kind == 2) {
;                         f32x4 cs, sn;
;                         if (MODE == 0) { const int pos = (wc & 1) ? gcol : grow; const float* tp = tab + pos * 16 + 4 * fq; cs = *(const f32x4*)tp; sn = *(const f32x4*)(tp + 1024); }
;                         else { const int pos = bj ? gcol : grow; const float* tp = tab + 2048 + pos * 64 + 16 * wc + 4 * fq; cs = *(const f32x4*)tp; sn = *(const f32x4*)(tp + 4096); }
;                         const f32x4 o0 = v0 * cs - v1 * sn, o1 = v0 * sn + v1 * cs; v0 = o0; v1 = o1;
;                     }
;                     if (kind == 2 || kind == 4) { v0 = v0 * ksc; v1 = v1 * ksc; }
;                     if (kind == 3) {
; #pragma unroll
;                         for (int e = 0; e < 4; ++e) { v0[e] = silu_f(v0[e]); v1[e] = silu_f(v1[e]); }
;                     }
;                     u32x4 w; w.x = cvt_pk_bf16(v0[0], v0[1]); w.y = cvt_pk_bf16(v0[2], v0[3]); w.z = cvt_pk_bf16(v1[0], v1[1]); w.w = cvt_pk_bf16(v1[2], v1[3]);
;                     *(u32x4*)(rowp + bj * 128) = w;
	global_store_dwordx4 v[32:33], v[20:23], off offset:256
	s_cbranch_vccz .LBB0_822
	s_cmp_gt_i32 s57, 3
	s_mov_b64 s[2:3], -1
	s_cbranch_scc0 .LBB0_823

; __device__ __forceinline__ unsigned cvt_pk_bf16(float lo, float hi) { unsigned r; asm volatile("v_cvt_pk_bf16_f32 %0, %1, %2" : "=v"(r) : "v"(lo), "v"(hi)); return r; }
; __device__ __forceinline__ float silu_f(float v) { return v * __builtin_amdgcn_rcpf(1.f + __builtin_amdgcn_exp2f(-v * LOG2E)); }
;     __device__ __forceinline__ void operator()(const f32x4 (&acc)[2][2][4][2], const pg8::Unit& u, int wr, int wc, int fr, int fq) const {
;     ...
;                 const int row = row0 + ai * 128 + m * 16;
;                 bf16_t* rowp = base + (size_t)row * ld + colt + wc * 32 + 8 * fq;
;                 const int t = row & 2047, grow = t >> 6, gcol = t & 63;
; #pragma unroll
;                 for (int bj = 0; bj < 2; ++bj) {
;                     f32x4 v0 = acc[ai][bj][m][0], v1 = acc[ai][bj][m][1];
;                     if (kind == 1 || kind == 2) {
;                         f32x4 cs, sn;
;                         if (MODE == 0) { const int pos = (wc & 1) ? gcol : grow; const float* tp = tab + pos * 16 + 4 * fq; cs = *(const f32x4*)tp; sn = *(const f32x4*)(tp + 1024); }
;                         else { const int pos = bj ? gcol : grow; const float* tp = tab + 2048 + pos * 64 + 16 * wc + 4 * fq; cs = *(const f32x4*)tp; sn = *(const f32x4*)(tp + 4096); }
;                         const f32x4 o0 = v0 * cs - v1 * sn, o1 = v0 * sn + v1 * cs; v0 = o0; v1 = o1;
;                     }
;                     if (kind == 2 || kind == 4) { v0 = v0 * ksc; v1 = v1 * ksc; }
;                     if (kind == 3) {
; #pragma unroll
;                         for (int e = 0; e < 4; ++e) { v0[e] = silu_f(v0[e]); v1[e] = silu_f(v1[e]); }
;                     }
;                     u32x4 w; w.x = cvt_pk_bf16(v0[0], v0[1]); w.y = cvt_pk_bf16(v0[2], v0[3]); w.z = cvt_pk_bf16(v1[0], v1[1]); w.w = cvt_pk_bf16(v1[2], v1[3]);
;                     *(u32x4*)(rowp + bj * 128) = w;
.LBB0_772:
	v_add_u32_e32 v16, 0xb0, v165
	v_mad_i64_i32 v[16:17], s[2:3], s66, v16, 0
	v_lshl_add_u64 v[16:17], v[16:17], 1, v[158:159]
	s_and_b64 vcc, exec, s[38:39]
	v_cvt_pk_bf16_f32 v12, v12, v13
	v_cvt_pk_bf16_f32 v13, v14, v15
	v_cvt_pk_bf16_f32 v14, v8, v9
	v_cvt_pk_bf16_f32 v15, v10, v11
	v_add_u32_e32 v230, 0x50100, v229
	v_lshl_add_u64 v[232:233], s[100:101], 0, v[230:231]
	v_cndmask_b32_e64 v16, v16, v232, s[98:99]
	v_cndmask_b32_e64 v17, v17, v233, s[98:99]

; __device__ __forceinline__ unsigned cvt_pk_bf16(float lo, float hi) { unsigned r; asm volatile("v_cvt_pk_bf16_f32 %0, %1, %2" : "=v"(r) : "v"(lo), "v"(hi)); return r; }
; __device__ __forceinline__ float silu_f(float v) { return v * __builtin_amdgcn_rcpf(1.f + __builtin_amdgcn_exp2f(-v * LOG2E)); }
;     __device__ __forceinline__ void operator()(const f32x4 (&acc)[2][2][4][2], const pg8::Unit& u, int wr, int wc, int fr, int fq) const {
;     ...
;                     if (kind == 1 || kind == 2) {
;                         f32x4 cs, sn;
;                         if (MODE == 0) { const int pos = (wc & 1) ? gcol : grow; const float* tp = tab + pos * 16 + 4 * fq; cs = *(const f32x4*)tp; sn = *(const f32x4*)(tp + 1024); }
;                         else { const int pos = bj ? gcol : grow; const float* tp = tab + 2048 + pos * 64 + 16 * wc + 4 * fq; cs = *(const f32x4*)tp; sn = *(const f32x4*)(tp + 4096); }
;                         const f32x4 o0 = v0 * cs - v1 * sn, o1 = v0 * sn + v1 * cs; v0 = o0; v1 = o1;
;                     }
;                     if (kind == 2 || kind == 4) { v0 = v0 * ksc; v1 = v1 * ksc; }
;                     if (kind == 3) {
; #pragma unroll
;                         for (int e = 0; e < 4; ++e) { v0[e] = silu_f(v0[e]); v1[e] = silu_f(v1[e]); }
;                     }
;                     u32x4 w; w.x = cvt_pk_bf16(v0[0], v0[1]); w.y = cvt_pk_bf16(v0[2], v0[3]); w.z = cvt_pk_bf16(v1[0], v1[1]); w.w = cvt_pk_bf16(v1[2], v1[3]);
;                     *(u32x4*)(rowp + bj * 128) = w;
	global_store_dwordx4 v[16:17], v[12:15], off
	s_cbranch_vccz .LBB0_825
	s_cmp_gt_i32 s57, 3
	s_mov_b64 s[2:3], -1
	s_cbranch_scc0 .LBB0_826

; __device__ __forceinline__ unsigned cvt_pk_bf16(float lo, float hi) { unsigned r; asm volatile("v_cvt_pk_bf16_f32 %0, %1, %2" : "=v"(r) : "v"(lo), "v"(hi)); return r; }
;     __device__ __forceinline__ void operator()(const f32x4 (&acc)[2][2][4][2], const pg8::Unit& u, int wr, int wc, int fr, int fq) const {
;     ...
;                     u32x4 w; w.x = cvt_pk_bf16(v0[0], v0[1]); w.y = cvt_pk_bf16(v0[2], v0[3]); w.z = cvt_pk_bf16(v1[0], v1[1]); w.w = cvt_pk_bf16(v1[2], v1[3]);
;                     *(u32x4*)(rowp + bj * 128) = w;
.LBB0_777:
	s_andn2_b64 vcc, exec, s[60:61]
	s_mov_b64 s[2:3], -1
	v_cvt_pk_bf16_f32 v4, v4, v5
	v_cvt_pk_bf16_f32 v5, v6, v7
	v_cvt_pk_bf16_f32 v6, v0, v1
	v_cvt_pk_bf16_f32 v7, v2, v3
	v_lshl_add_u64 v[16:17], v[16:17], 0, v[234:235]

; __device__ __forceinline__ unsigned cvt_pk_bf16(float lo, float hi) { unsigned r; asm volatile("v_cvt_pk_bf16_f32 %0, %1, %2" : "=v"(r) : "v"(lo), "v"(hi)); return r; }
; #define PG8_BAR __builtin_amdgcn_s_barrier()
; template <class Epi, class Sched, bool ALIGN_EPI = false, bool SP2 = false>
; __device__ __forceinline__ void gemm_phase(PG8_LAS unsigned char* lds, const Gemm g, const Sched& S, const Epi& E) {
;     ...
;         if (!has_next) break;
; #pragma unroll
;         for (int a = 0; a < 2; ++a)
; #pragma unroll
;             for (int b = 0; b < 2; ++b)
; #pragma unroll
;                 for (int m = 0; m < 4; ++m)
; #pragma unroll
;                     for (int n = 0; n < 2; ++n) acc[a][b][m][n] = (f32x4){0.f, 0.f, 0.f, 0.f};
;         cur = nxt; cA = nA; cB = nB; ++ui;
;         if constexpr (ALIGN_EPI) { if (wr == 1) PG8_BAR; }
;     __device__ __forceinline__ void operator()(const f32x4 (&acc)[2][2][4][2], const pg8::Unit& u, int wr, int wc, int fr, int fq) const {
;     ...
;                     u32x4 w; w.x = cvt_pk_bf16(v0[0], v0[1]); w.y = cvt_pk_bf16(v0[2], v0[3]); w.z = cvt_pk_bf16(v1[0], v1[1]); w.w = cvt_pk_bf16(v1[2], v1[3]);
;                     *(u32x4*)(rowp + bj * 128) = w;
	global_store_dwordx4 v[16:17], v[4:7], off offset:256
	s_cbranch_vccnz .LBB0_678
	s_andn2_b64 vcc, exec, s[76:77]
	s_cbranch_vccnz .LBB0_677
	s_barrier
	s_branch .LBB0_677

; __global__ void __launch_bounds__(512, 2) trunk_fwd(Params p) {
;     extern __shared__ __attribute__((aligned(16))) unsigned char smem[];
	.amdhsa_kernel _Z9trunk_fwd6Params
		.amdhsa_group_segment_fixed_size 0
		.amdhsa_private_segment_fixed_size 0
		.amdhsa_kernarg_size 432
		.amdhsa_user_sgpr_count 2
		.amdhsa_user_sgpr_dispatch_ptr 0
		.amdhsa_user_sgpr_queue_ptr 0
		.amdhsa_user_sgpr_kernarg_segment_ptr 1
		.amdhsa_user_sgpr_dispatch_id 0
		.amdhsa_user_sgpr_kernarg_preload_length 0
		.amdhsa_user_sgpr_kernarg_preload_offset 0
		.amdhsa_user_sgpr_private_segment_size 0
		.amdhsa_uses_dynamic_stack 0
		.amdhsa_enable_private_segment 0
		.amdhsa_system_sgpr_workgroup_id_x 1
		.amdhsa_system_sgpr_workgroup_id_y 0
		.amdhsa_system_sgpr_workgroup_id_z 0
		.amdhsa_system_sgpr_workgroup_info 0
		.amdhsa_system_vgpr_workitem_id 2
		.amdhsa_next_free_vgpr 256
		.amdhsa_next_free_sgpr 102
		.amdhsa_accum_offset 256
		.amdhsa_reserve_vcc 1
		.amdhsa_float_round_mode_32 0
		.amdhsa_float_round_mode_16_64 0
		.amdhsa_float_denorm_mode_32 3
		.amdhsa_float_denorm_mode_16_64 3
		.amdhsa_dx10_clamp 1
		.amdhsa_ieee_mode 1
		.amdhsa_fp16_overflow 0
		.amdhsa_tg_split 0
		.amdhsa_exception_fp_ieee_invalid_op 0
		.amdhsa_exception_fp_denorm_src 0
		.amdhsa_exception_fp_ieee_div_zero 0
		.amdhsa_exception_fp_ieee_overflow 0
		.amdhsa_exception_fp_ieee_underflow 0
		.amdhsa_exception_fp_ieee_inexact 0
		.amdhsa_exception_int_div_zero 0
	.end_amdhsa_kernel

; __global__ void __launch_bounds__(512, 2) trunk_fwd(Params p) {
;     extern __shared__ __attribute__((aligned(16))) unsigned char smem[];
amdhsa.kernels:
  - .agpr_count:     0
    .args:
      - .offset:         0
        .size:           176
        .value_kind:     by_value
      - .offset:         176
        .size:           4
        .value_kind:     hidden_block_count_x
      - .offset:         180
        .size:           4
        .value_kind:     hidden_block_count_y
      - .offset:         184
        .size:           4
        .value_kind:     hidden_block_count_z
      - .offset:         188
        .size:           2
        .value_kind:     hidden_group_size_x
      - .offset:         190
        .size:           2
        .value_kind:     hidden_group_size_y
      - .offset:         192
        .size:           2
        .value_kind:     hidden_group_size_z
      - .offset:         194
        .size:           2
        .value_kind:     hidden_remainder_x
      - .offset:         196
        .size:           2
        .value_kind:     hidden_remainder_y
      - .offset:         198
        .size:           2
        .value_kind:     hidden_remainder_z
      - .offset:         216
        .size:           8
        .value_kind:     hidden_global_offset_x
      - .offset:         224
        .size:           8
        .value_kind:     hidden_global_offset_y
      - .offset:         232
        .size:           8
        .value_kind:     hidden_global_offset_z
      - .offset:         240
        .size:           2
        .value_kind:     hidden_grid_dims
      - .offset:         264
        .size:           8
        .value_kind:     hidden_multigrid_sync_arg
      - .offset:         296
        .size:           4
        .value_kind:     hidden_dynamic_lds_size
    .group_segment_fixed_size: 0
    .kernarg_segment_align: 8
    .kernarg_segment_size: 432
    .language:       OpenCL C
    .language_version:
      - 2
      - 0
    .max_flat_workgroup_size: 512
    .name:           _Z9trunk_fwd6Params
    .private_segment_fixed_size: 0
    .sgpr_count:     108
    .sgpr_spill_count: 121
    .symbol:         _Z9trunk_fwd6Params.kd
    .uniform_work_group_size: 1
    .uses_dynamic_stack: false
    .vgpr_count:     256
    .vgpr_spill_count: 0
    .wavefront_size: 64
